# tail transposes (depth-2, nt) plus two-barrier staggered diff-attention loop
# speedup vs baseline: 1.0366x; 1.0079x over previous
.LBB0_1231:
	s_and_b64 vcc, exec, s[4:5]
	s_cbranch_vccz .LBB0_1237
	v_mov_b32_e32 v210, v214
	s_lshl_b64 s[2:3], s[2:3], 1
	v_and_b32_e32 v205, 31, v210
	v_ashrrev_i32_e32 v16, 5, v210
	v_or_b32_e32 v0, s66, v205
	v_lshlrev_b64 v[2:3], 14, v[0:1]
	v_lshlrev_b32_e32 v4, 3, v16
	v_lshl_add_u64 v[2:3], s[42:43], 0, v[2:3]
	v_ashrrev_i32_e32 v5, 31, v4
	v_lshl_add_u64 v[2:3], v[4:5], 1, v[2:3]
	global_load_dwordx4 v[190:193], v[2:3], off offset:256
	global_load_dwordx4 v[186:189], v[2:3], off offset:288
	global_load_dwordx4 v[182:185], v[2:3], off offset:320
	global_load_dwordx4 v[178:181], v[2:3], off offset:352
	global_load_dwordx4 v[174:177], v[2:3], off offset:384
	global_load_dwordx4 v[170:173], v[2:3], off offset:416
	global_load_dwordx4 v[166:169], v[2:3], off offset:448
	global_load_dwordx4 v[162:165], v[2:3], off offset:480
	v_lshlrev_b32_e32 v17, 4, v210
	v_lshlrev_b32_e32 v3, 1, v210
	v_and_b32_e32 v2, 0xc0, v17
	v_and_b32_e32 v3, 32, v3
	v_add_u32_e32 v7, s65, v210
	v_add3_u32 v3, 0, v2, v3
	v_ashrrev_i32_e32 v2, 4, v7
	v_xor_b32_e32 v4, v2, v210
	v_lshlrev_b32_e32 v2, 13, v2
	v_lshlrev_b32_e32 v4, 3, v4
	v_add_u32_e32 v8, 0x200, v7
	v_and_or_b32 v2, v4, s60, v2
	v_ashrrev_i32_e32 v4, 4, v8
	v_xor_b32_e32 v6, v4, v210
	v_lshlrev_b32_e32 v4, 13, v4
	v_lshlrev_b32_e32 v6, 3, v6
	v_and_or_b32 v4, v6, s60, v4
	v_bfe_u32 v6, v210, 2, 2
	v_lshrrev_b32_e32 v9, 1, v210
	v_and_or_b32 v9, v9, 8, v6
	v_ashrrev_i32_e32 v6, 5, v7
	v_and_b32_e32 v10, 0x7fff0, v6
	v_lshrrev_b32_e32 v6, 1, v6
	v_and_b32_e32 v6, 4, v6
	v_ashrrev_i32_e32 v8, 5, v8
	v_or3_b32 v6, v10, v6, v9
	v_and_b32_e32 v10, 0x7fff0, v8
	v_lshrrev_b32_e32 v8, 1, v8
	v_and_b32_e32 v8, 4, v8
	v_or3_b32 v8, v10, v8, v9
	v_add_u32_e32 v10, 0x400, v7
	v_ashrrev_i32_e32 v10, 5, v10
	v_lshlrev_b32_e32 v0, 3, v210
	v_and_b32_e32 v11, 0xe0, v7
	v_and_b32_e32 v12, 0x7fff0, v10
	v_lshrrev_b32_e32 v10, 1, v10
	v_add_u32_e32 v7, 0x600, v7
	v_and_b32_e32 v5, 0x100, v0
	v_and_b32_e32 v0, 24, v0
	v_and_b32_e32 v10, 4, v10
	v_ashrrev_i32_e32 v7, 5, v7
	v_or3_b32 v10, v12, v10, v9
	v_and_b32_e32 v12, 0x7fff0, v7
	v_lshrrev_b32_e32 v7, 1, v7
	v_add3_u32 v216, v3, v5, v0
	v_ashrrev_i32_e32 v3, 31, v2
	v_and_b32_e32 v7, 4, v7
	v_lshlrev_b64 v[2:3], 1, v[2:3]
	v_lshlrev_b32_e32 v6, 13, v6
	v_or3_b32 v7, v12, v7, v9
	v_lshl_add_u64 v[14:15], s[44:45], 0, v[2:3]
	v_ashrrev_i32_e32 v5, 31, v4
	s_mov_b32 m0, s90
	v_or3_b32 v6, v6, v11, v0
	v_lshlrev_b32_e32 v8, 13, v8
	v_lshlrev_b32_e32 v7, 13, v7
	v_lshl_add_u64 v[14:15], v[14:15], 0, s[2:3]
	v_lshlrev_b64 v[4:5], 1, v[4:5]
	s_add_u32 s5, s44, s2
	v_or3_b32 v8, v8, v11, v0
	v_lshlrev_b32_e32 v10, 13, v10
	v_or3_b32 v12, v7, v11, v0
	global_load_lds_dwordx4 v[14:15], off
	v_lshl_add_u64 v[14:15], s[44:45], 0, v[4:5]
	v_ashrrev_i32_e32 v7, 31, v6
	s_addc_u32 s6, s45, s3
	v_or3_b32 v10, v10, v11, v0
	v_lshl_add_u64 v[14:15], v[14:15], 0, s[2:3]
	s_add_i32 m0, s90, 0x2000
	v_lshlrev_b64 v[6:7], 1, v[6:7]
	v_ashrrev_i32_e32 v9, 31, v8
	global_load_lds_dwordx4 v[14:15], off
	v_lshl_add_u64 v[14:15], s[40:41], 0, v[6:7]
	s_mov_b32 m0, s94
	v_lshlrev_b64 v[8:9], 1, v[8:9]
	v_ashrrev_i32_e32 v11, 31, v10
	global_load_lds_dwordx4 v[14:15], off
	v_lshl_add_u64 v[14:15], s[40:41], 0, v[8:9]
	s_add_i32 m0, s90, 0xe000
	v_lshlrev_b64 v[10:11], 1, v[10:11]
	global_load_lds_dwordx4 v[14:15], off
	v_lshl_add_u64 v[14:15], s[40:41], 0, v[10:11]
	s_add_i32 m0, s94, 0x4000
	v_ashrrev_i32_e32 v13, 31, v12
	global_load_lds_dwordx4 v[14:15], off
	s_add_i32 m0, s94, 0x6000
	v_lshlrev_b64 v[12:13], 1, v[12:13]
	s_add_u32 s2, s5, 0x100000
	v_lshl_add_u64 v[14:15], s[40:41], 0, v[12:13]
	s_addc_u32 s3, s6, 0
	global_load_lds_dwordx4 v[14:15], off
	v_lshl_add_u64 v[14:15], s[2:3], 0, v[2:3]
	s_add_i32 m0, s90, 0x4000
	v_lshlrev_b32_e32 v0, 4, v16
	global_load_lds_dwordx4 v[14:15], off
	s_add_i32 m0, s90, 0x6000
	v_lshl_add_u64 v[14:15], s[2:3], 0, v[4:5]
	s_add_u32 s2, s40, 0x100000
	s_addc_u32 s3, s41, 0
	global_load_lds_dwordx4 v[14:15], off
	v_lshl_add_u64 v[14:15], s[2:3], 0, v[6:7]
	s_add_i32 m0, s90, 0x14000
	v_mov_b32_e32 v211, 0
	global_load_lds_dwordx4 v[14:15], off
	v_lshl_add_u64 v[14:15], s[2:3], 0, v[8:9]
	s_add_i32 m0, s90, 0x16000
	s_mov_b32 s4, 0
	global_load_lds_dwordx4 v[14:15], off
	v_lshl_add_u64 v[14:15], s[2:3], 0, v[10:11]
	s_add_i32 m0, s90, 0x18000
	v_lshl_add_u32 v217, v205, 8, 0
	global_load_lds_dwordx4 v[14:15], off
	v_lshl_add_u64 v[14:15], s[2:3], 0, v[12:13]
	s_add_i32 m0, s90, 0x1a000
	s_add_u32 s5, s38, s36
	global_load_lds_dwordx4 v[14:15], off
	v_add_u32_e32 v14, 32, v0
	v_bitop3_b32 v224, v14, v17, s51 bitop3:0x78
	v_add_u32_e32 v14, 64, v0
	v_bitop3_b32 v223, v14, v17, s51 bitop3:0x78
	v_add_u32_e32 v14, 0x60, v0
	s_addc_u32 s6, s39, s37
	v_bitop3_b32 v222, v14, v17, s51 bitop3:0x78
	v_add_u32_e32 v14, 0x80, v0
	s_add_u32 s2, s97, s5
	v_bitop3_b32 v221, v14, v17, s51 bitop3:0x78
	v_add_u32_e32 v14, 0xa0, v0
	s_addc_u32 s3, s53, s6
	v_bitop3_b32 v220, v14, v17, s51 bitop3:0x78
	v_add_u32_e32 v14, 0xc0, v0
	s_waitcnt vmcnt(0)
	v_lshl_add_u64 v[194:195], s[2:3], 0, v[2:3]
	v_lshl_add_u64 v[196:197], s[2:3], 0, v[4:5]
	s_add_u32 s2, s54, s5
	v_bitop3_b32 v219, v14, v17, s51 bitop3:0x78
	v_add_u32_e32 v14, 0xe0, v0
	s_addc_u32 s3, s55, s6
	v_bitop3_b32 v225, v0, v17, s51 bitop3:0x78
	v_bitop3_b32 v218, v14, v17, s51 bitop3:0x78
	v_lshl_add_u64 v[198:199], s[2:3], 0, v[6:7]
	v_lshl_add_u64 v[200:201], s[2:3], 0, v[8:9]
	v_lshl_add_u64 v[202:203], s[2:3], 0, v[10:11]
	v_lshl_add_u64 v[208:209], s[2:3], 0, v[12:13]
	s_mov_b64 s[2:3], 0
	v_mov_b32_e32 v2, 0
	v_mov_b32_e32 v3, v211
	v_mov_b32_e32 v4, v211
	v_mov_b32_e32 v5, v211
	v_mov_b32_e32 v6, v211
	v_mov_b32_e32 v7, v211
	v_mov_b32_e32 v8, v211
	v_mov_b32_e32 v9, v211
	v_mov_b32_e32 v10, v211
	v_mov_b32_e32 v11, v211
	v_mov_b32_e32 v12, v211
	v_mov_b32_e32 v13, v211
	v_mov_b32_e32 v14, v211
	v_mov_b32_e32 v15, v211
	v_mov_b32_e32 v16, v211
	v_mov_b32_e32 v17, v211
	v_mov_b32_e32 v18, 0
	v_mov_b32_e32 v19, v211
	v_mov_b32_e32 v20, v211
	v_mov_b32_e32 v21, v211
	v_mov_b32_e32 v22, v211
	v_mov_b32_e32 v23, v211
	v_mov_b32_e32 v24, v211
	v_mov_b32_e32 v25, v211
	v_mov_b32_e32 v26, v211
	v_mov_b32_e32 v27, v211
	v_mov_b32_e32 v28, v211
	v_mov_b32_e32 v29, v211
	v_mov_b32_e32 v30, v211
	v_mov_b32_e32 v31, v211
	v_mov_b32_e32 v32, v211
	v_mov_b32_e32 v33, v211
	v_mov_b32_e32 v34, 0
	v_mov_b32_e32 v35, v211
	v_mov_b32_e32 v36, v211
	v_mov_b32_e32 v37, v211
	v_mov_b32_e32 v38, v211
	v_mov_b32_e32 v39, v211
	v_mov_b32_e32 v40, v211
	v_mov_b32_e32 v41, v211
	v_mov_b32_e32 v42, v211
	v_mov_b32_e32 v43, v211
	v_mov_b32_e32 v44, v211
	v_mov_b32_e32 v45, v211
	v_mov_b32_e32 v46, v211
	v_mov_b32_e32 v47, v211
	v_mov_b32_e32 v48, v211
	v_mov_b32_e32 v49, v211
	v_mov_b32_e32 v50, 0
	v_mov_b32_e32 v51, v211
	v_mov_b32_e32 v52, v211
	v_mov_b32_e32 v53, v211
	v_mov_b32_e32 v54, v211
	v_mov_b32_e32 v55, v211
	v_mov_b32_e32 v56, v211
	v_mov_b32_e32 v57, v211
	v_mov_b32_e32 v58, v211
	v_mov_b32_e32 v59, v211
	v_mov_b32_e32 v60, v211
	v_mov_b32_e32 v61, v211
	v_mov_b32_e32 v62, v211
	v_mov_b32_e32 v63, v211
	v_mov_b32_e32 v64, v211
	v_mov_b32_e32 v65, v211
	v_mov_b32_e32 v66, 0
	v_mov_b32_e32 v67, v211
	v_mov_b32_e32 v68, v211
	v_mov_b32_e32 v69, v211
	v_mov_b32_e32 v70, v211
	v_mov_b32_e32 v71, v211
	v_mov_b32_e32 v72, v211
	v_mov_b32_e32 v73, v211
	v_mov_b32_e32 v74, v211
	v_mov_b32_e32 v75, v211
	v_mov_b32_e32 v76, v211
	v_mov_b32_e32 v77, v211
	v_mov_b32_e32 v78, v211
	v_mov_b32_e32 v79, v211
	v_mov_b32_e32 v80, v211
	v_mov_b32_e32 v81, v211
	v_mov_b32_e32 v82, 0
	v_mov_b32_e32 v83, v211
	v_mov_b32_e32 v84, v211
	v_mov_b32_e32 v85, v211
	v_mov_b32_e32 v86, v211
	v_mov_b32_e32 v87, v211
	v_mov_b32_e32 v88, v211
	v_mov_b32_e32 v89, v211
	v_mov_b32_e32 v90, v211
	v_mov_b32_e32 v91, v211
	v_mov_b32_e32 v92, v211
	v_mov_b32_e32 v93, v211
	v_mov_b32_e32 v94, v211
	v_mov_b32_e32 v95, v211
	v_mov_b32_e32 v96, v211
	v_mov_b32_e32 v97, v211
	v_mov_b32_e32 v98, 0
	v_mov_b32_e32 v99, v211
	v_mov_b32_e32 v100, v211
	v_mov_b32_e32 v101, v211
	v_mov_b32_e32 v102, v211
	v_mov_b32_e32 v103, v211
	v_mov_b32_e32 v104, v211
	v_mov_b32_e32 v105, v211
	v_mov_b32_e32 v106, v211
	v_mov_b32_e32 v107, v211
	v_mov_b32_e32 v108, v211
	v_mov_b32_e32 v109, v211
	v_mov_b32_e32 v110, v211
	v_mov_b32_e32 v111, v211
	v_mov_b32_e32 v112, v211
	v_mov_b32_e32 v113, v211
	v_mov_b32_e32 v114, 0
	v_mov_b32_e32 v115, v211
	v_mov_b32_e32 v116, v211
	v_mov_b32_e32 v117, v211
	v_mov_b32_e32 v118, v211
	v_mov_b32_e32 v119, v211
	v_mov_b32_e32 v120, v211
	v_mov_b32_e32 v121, v211
	v_mov_b32_e32 v122, v211
	v_mov_b32_e32 v123, v211
	v_mov_b32_e32 v124, v211
	v_mov_b32_e32 v125, v211
	v_mov_b32_e32 v126, v211
	v_mov_b32_e32 v127, v211
	v_mov_b32_e32 v128, v211
	v_mov_b32_e32 v129, v211
	s_cmp_lt_u32 s66, 0x80
	s_cbranch_scc1 .Lst1_a
	s_barrier
.Lst1_a:
.LBB0_1233:
	s_waitcnt vmcnt(6)
	s_waitcnt lgkmcnt(0)
	s_barrier
	v_lshl_add_u32 v234, s4, 14, v217
	v_add_u32_e32 v134, v234, v225
	v_add_u32_e32 v230, v234, v224
	ds_read_b128 v[130:133], v134
	ds_read_b128 v[134:137], v134 offset:8192
	s_waitcnt lgkmcnt(0)
	v_mfma_f32_32x32x16_bf16 v[146:161], v[130:133], v[190:193], 0
	ds_read_b128 v[226:229], v230
	ds_read_b128 v[230:233], v230 offset:8192
	s_add_i32 s5, s4, 1
	s_cmp_lg_u32 s4, 2
	v_mfma_f32_32x32x16_bf16 v[130:145], v[134:137], v[190:193], 0
	s_waitcnt lgkmcnt(0)
	v_mfma_f32_32x32x16_bf16 v[130:145], v[230:233], v[186:189], v[130:145]
	v_add_u32_e32 v230, v234, v223
	v_mfma_f32_32x32x16_bf16 v[146:161], v[226:229], v[186:189], v[146:161]
	ds_read_b128 v[226:229], v230
	ds_read_b128 v[230:233], v230 offset:8192
	s_waitcnt lgkmcnt(0)
	v_mfma_f32_32x32x16_bf16 v[130:145], v[230:233], v[182:185], v[130:145]
	v_add_u32_e32 v230, v234, v222
	v_mfma_f32_32x32x16_bf16 v[146:161], v[226:229], v[182:185], v[146:161]
	ds_read_b128 v[226:229], v230
	ds_read_b128 v[230:233], v230 offset:8192
	s_waitcnt lgkmcnt(0)
	v_mfma_f32_32x32x16_bf16 v[130:145], v[230:233], v[178:181], v[130:145]
	v_add_u32_e32 v230, v234, v221
	v_mfma_f32_32x32x16_bf16 v[146:161], v[226:229], v[178:181], v[146:161]
	ds_read_b128 v[226:229], v230
	ds_read_b128 v[230:233], v230 offset:8192
	s_waitcnt lgkmcnt(0)
	v_mfma_f32_32x32x16_bf16 v[130:145], v[230:233], v[174:177], v[130:145]
	v_add_u32_e32 v230, v234, v220
	v_mfma_f32_32x32x16_bf16 v[146:161], v[226:229], v[174:177], v[146:161]
	ds_read_b128 v[226:229], v230
	ds_read_b128 v[230:233], v230 offset:8192
	s_waitcnt lgkmcnt(0)
	v_mfma_f32_32x32x16_bf16 v[130:145], v[230:233], v[170:173], v[130:145]
	v_add_u32_e32 v230, v234, v219
	v_mfma_f32_32x32x16_bf16 v[146:161], v[226:229], v[170:173], v[146:161]
	ds_read_b128 v[226:229], v230
	ds_read_b128 v[230:233], v230 offset:8192
	s_waitcnt lgkmcnt(0)
	v_mfma_f32_32x32x16_bf16 v[130:145], v[230:233], v[166:169], v[130:145]
	v_add_u32_e32 v230, v234, v218
	v_mfma_f32_32x32x16_bf16 v[146:161], v[226:229], v[166:169], v[146:161]
	ds_read_b128 v[226:229], v230
	ds_read_b128 v[230:233], v230 offset:8192
	s_waitcnt lgkmcnt(0)
	v_mfma_f32_32x32x16_bf16 v[130:145], v[230:233], v[162:165], v[130:145]
	v_mfma_f32_32x32x16_bf16 v[146:161], v[226:229], v[162:165], v[146:161]
	s_nop 10
	v_fmamk_f32 v138, v138, 0x3e0293ee, v215
	v_fmamk_f32 v139, v139, 0x3e0293ee, v215
	v_fmamk_f32 v140, v140, 0x3e0293ee, v215
	v_fmamk_f32 v141, v141, 0x3e0293ee, v215
	v_fmamk_f32 v142, v142, 0x3e0293ee, v215
	v_exp_f32_e32 v226, v138
	v_fmamk_f32 v130, v130, 0x3e0293ee, v215
	v_fmamk_f32 v138, v155, 0x3e0293ee, v215
	v_exp_f32_e32 v155, v139
	v_fmamk_f32 v139, v156, 0x3e0293ee, v215
	v_exp_f32_e32 v156, v140
	v_fmamk_f32 v140, v157, 0x3e0293ee, v215
	v_exp_f32_e32 v157, v141
	v_fmamk_f32 v141, v158, 0x3e0293ee, v215
	v_exp_f32_e32 v158, v142
	v_fmamk_f32 v142, v159, 0x3e0293ee, v215
	v_fmamk_f32 v146, v146, 0x3e0293ee, v215
	v_exp_f32_e32 v159, v142
	v_fmamk_f32 v142, v143, 0x3e0293ee, v215
	v_exp_f32_e32 v146, v146
	v_fmamk_f32 v147, v147, 0x3e0293ee, v215
	v_exp_f32_e32 v227, v142
	v_fmamk_f32 v142, v160, 0x3e0293ee, v215
	v_exp_f32_e32 v147, v147
	v_fmamk_f32 v148, v148, 0x3e0293ee, v215
	v_exp_f32_e32 v160, v142
	v_fmamk_f32 v142, v144, 0x3e0293ee, v215
	v_exp_f32_e32 v148, v148
	v_fmamk_f32 v149, v149, 0x3e0293ee, v215
	v_exp_f32_e32 v228, v142
	v_fmamk_f32 v142, v161, 0x3e0293ee, v215
	v_exp_f32_e32 v149, v149
	v_fmamk_f32 v150, v150, 0x3e0293ee, v215
	v_exp_f32_e32 v161, v142
	v_fmamk_f32 v142, v145, 0x3e0293ee, v215
	v_exp_f32_e32 v150, v150
	v_fmamk_f32 v151, v151, 0x3e0293ee, v215
	v_exp_f32_e32 v229, v142
	v_add_f32_e32 v142, 0, v146
	v_exp_f32_e32 v151, v151
	v_fmamk_f32 v152, v152, 0x3e0293ee, v215
	v_add_f32_e32 v142, v147, v142
	v_exp_f32_e32 v152, v152
	v_fmamk_f32 v153, v153, 0x3e0293ee, v215
	v_add_f32_e32 v142, v148, v142
	v_exp_f32_e32 v153, v153
	v_fmamk_f32 v154, v154, 0x3e0293ee, v215
	v_add_f32_e32 v142, v149, v142
	v_exp_f32_e32 v154, v154
	v_add_f32_e32 v142, v150, v142
	v_exp_f32_e32 v138, v138
	v_add_f32_e32 v142, v151, v142
	v_exp_f32_e32 v139, v139
	v_add_f32_e32 v142, v152, v142
	v_exp_f32_e32 v140, v140
	v_add_f32_e32 v142, v153, v142
	v_exp_f32_e32 v141, v141
	v_add_f32_e32 v142, v154, v142
	v_add_f32_e32 v142, v138, v142
	v_add_f32_e32 v142, v139, v142
	v_add_f32_e32 v142, v140, v142
	v_exp_f32_e32 v130, v130
	v_fmamk_f32 v131, v131, 0x3e0293ee, v215
	v_add_f32_e32 v142, v141, v142
	v_exp_f32_e32 v131, v131
	v_fmamk_f32 v132, v132, 0x3e0293ee, v215
	v_add_f32_e32 v142, v159, v142
	v_exp_f32_e32 v132, v132
	v_fmamk_f32 v133, v133, 0x3e0293ee, v215
	v_add_f32_e32 v142, v160, v142
	v_exp_f32_e32 v133, v133
	v_fmamk_f32 v134, v134, 0x3e0293ee, v215
	v_add_f32_e32 v142, v161, v142
	v_exp_f32_e32 v134, v134
	v_fmamk_f32 v135, v135, 0x3e0293ee, v215
	v_add_f32_e32 v142, v130, v142
	v_exp_f32_e32 v135, v135
	v_fmamk_f32 v136, v136, 0x3e0293ee, v215
	v_add_f32_e32 v142, v131, v142
	v_exp_f32_e32 v136, v136
	v_fmamk_f32 v137, v137, 0x3e0293ee, v215
	v_add_f32_e32 v142, v132, v142
	v_exp_f32_e32 v137, v137
	v_add_f32_e32 v142, v133, v142
	v_add_f32_e32 v142, v134, v142
	v_add_f32_e32 v142, v135, v142
	v_add_f32_e32 v142, v136, v142
	v_add_f32_e32 v142, v137, v142
	v_add_f32_e32 v142, v226, v142
	v_add_f32_e32 v142, v155, v142
	v_add_f32_e32 v142, v156, v142
	v_add_f32_e32 v142, v157, v142
	v_add_f32_e32 v142, v158, v142
	v_add_f32_e32 v142, v227, v142
	v_add_f32_e32 v142, v228, v142
	v_add_f32_e32 v142, v229, v142
	v_mov_b32_e32 v143, v142
	s_nop 1
	v_permlane32_swap_b32_e32 v142, v143
	v_add_f32_e32 v142, v142, v143
	v_add_f32_e32 v211, v211, v142
	v_cvt_pk_bf16_f32 v142, v146, v147
	v_cvt_pk_bf16_f32 v143, v148, v149
	v_cvt_pk_bf16_f32 v144, v150, v151
	v_cvt_pk_bf16_f32 v145, v152, v153
	s_nop 0
	v_permlane32_swap_b32_e32 v142, v144
	v_permlane32_swap_b32_e32 v143, v145
	v_lshl_add_u32 v146, s4, 15, v216
	v_cvt_pk_bf16_f32 v138, v154, v138
	v_cvt_pk_bf16_f32 v139, v139, v140
	v_cvt_pk_bf16_f32 v140, v141, v159
	v_cvt_pk_bf16_f32 v141, v160, v161
	v_cvt_pk_bf16_f32 v130, v130, v131
	v_cvt_pk_bf16_f32 v131, v132, v133
	v_cvt_pk_bf16_f32 v132, v134, v135
	v_cvt_pk_bf16_f32 v133, v136, v137
	v_cvt_pk_bf16_f32 v134, v226, v155
	v_cvt_pk_bf16_f32 v135, v156, v157
	v_cvt_pk_bf16_f32 v136, v158, v227
	v_cvt_pk_bf16_f32 v137, v228, v229
	v_add_u32_e32 v152, 0xc000, v146
	s_waitcnt vmcnt(0)
	s_barrier
	s_add_i32 s98, s4, -1
	s_cmp_eq_u32 s4, 0
	s_cselect_b32 s98, 2, s98
	s_lshl_b32 s99, s98, 14
	s_add_i32 s99, s90, s99
	s_lshl_b32 s98, s98, 15
	s_add_i32 s98, s90, s98
	v_lshl_add_u64 v[236:237], v[194:195], 0, s[2:3]
	s_mov_b32 m0, s99
	s_nop 0
	global_load_lds_dwordx4 v[236:237], off
	v_lshl_add_u64 v[236:237], v[196:197], 0, s[2:3]
	s_add_i32 m0, s99, 0x2000
	s_nop 0
	global_load_lds_dwordx4 v[236:237], off
	v_lshl_add_u64 v[236:237], v[198:199], 0, s[2:3]
	s_add_i32 m0, s98, 0xc000
	s_nop 0
	global_load_lds_dwordx4 v[236:237], off
	v_lshl_add_u64 v[236:237], v[200:201], 0, s[2:3]
	s_add_i32 m0, s98, 0xe000
	s_nop 0
	global_load_lds_dwordx4 v[236:237], off
	v_lshl_add_u64 v[236:237], v[202:203], 0, s[2:3]
	s_add_i32 m0, s98, 0x10000
	s_nop 0
	global_load_lds_dwordx4 v[236:237], off
	v_lshl_add_u64 v[236:237], v[208:209], 0, s[2:3]
	s_add_i32 m0, s98, 0x12000
	s_nop 0
	global_load_lds_dwordx4 v[236:237], off
	s_cmp_lg_u32 s4, 2
	ds_read_b64_tr_b16 v[148:149], v146 offset:49152
	ds_read_b64_tr_b16 v[150:151], v146 offset:53248
	ds_read_b64_tr_b16 v[154:155], v146 offset:57344
	ds_read_b64_tr_b16 v[156:157], v146 offset:61440
	ds_read_b64_tr_b16 v[158:159], v152 offset:16384
	ds_read_b64_tr_b16 v[160:161], v152 offset:20480
	ds_read_b64_tr_b16 v[226:227], v152 offset:24576
	ds_read_b64_tr_b16 v[228:229], v152 offset:28672
	s_waitcnt lgkmcnt(0)
	v_mfma_f32_32x32x16_bf16 v[114:129], v[142:145], v[148:151], v[114:129]
	v_permlane32_swap_b32_e32 v138, v140
	v_permlane32_swap_b32_e32 v139, v141
	v_permlane32_swap_b32_e32 v130, v132
	v_permlane32_swap_b32_e32 v131, v133
	v_mfma_f32_32x32x16_bf16 v[114:129], v[138:141], v[154:157], v[114:129]
	v_permlane32_swap_b32_e32 v134, v136
	v_permlane32_swap_b32_e32 v135, v137
	s_cselect_b32 s4, s5, 0
	s_add_u32 s2, s2, 0x100000
	s_addc_u32 s3, s3, 0
	v_mfma_f32_32x32x16_bf16 v[114:129], v[130:133], v[158:161], v[114:129]
	s_cmp_eq_u32 s2, 0x2200000
	v_mfma_f32_32x32x16_bf16 v[114:129], v[134:137], v[226:229], v[114:129]
	ds_read_b64_tr_b16 v[148:149], v146 offset:49664
	ds_read_b64_tr_b16 v[150:151], v146 offset:53760
	ds_read_b64_tr_b16 v[154:155], v146 offset:57856
	ds_read_b64_tr_b16 v[156:157], v146 offset:61952
	ds_read_b64_tr_b16 v[158:159], v152 offset:16896
	ds_read_b64_tr_b16 v[160:161], v152 offset:20992
	ds_read_b64_tr_b16 v[226:227], v152 offset:25088
	ds_read_b64_tr_b16 v[228:229], v152 offset:29184
	s_waitcnt lgkmcnt(0)
	v_mfma_f32_32x32x16_bf16 v[98:113], v[142:145], v[148:151], v[98:113]
	v_mfma_f32_32x32x16_bf16 v[98:113], v[138:141], v[154:157], v[98:113]
	v_mfma_f32_32x32x16_bf16 v[98:113], v[130:133], v[158:161], v[98:113]
	v_mfma_f32_32x32x16_bf16 v[98:113], v[134:137], v[226:229], v[98:113]
	ds_read_b64_tr_b16 v[148:149], v146 offset:50176
	ds_read_b64_tr_b16 v[150:151], v146 offset:54272
	ds_read_b64_tr_b16 v[154:155], v146 offset:58368
	ds_read_b64_tr_b16 v[156:157], v146 offset:62464
	ds_read_b64_tr_b16 v[158:159], v152 offset:17408
	ds_read_b64_tr_b16 v[160:161], v152 offset:21504
	ds_read_b64_tr_b16 v[226:227], v152 offset:25600
	ds_read_b64_tr_b16 v[228:229], v152 offset:29696
	s_waitcnt lgkmcnt(0)
	v_mfma_f32_32x32x16_bf16 v[82:97], v[142:145], v[148:151], v[82:97]
	v_mfma_f32_32x32x16_bf16 v[82:97], v[138:141], v[154:157], v[82:97]
	v_mfma_f32_32x32x16_bf16 v[82:97], v[130:133], v[158:161], v[82:97]
	v_mfma_f32_32x32x16_bf16 v[82:97], v[134:137], v[226:229], v[82:97]
	ds_read_b64_tr_b16 v[148:149], v146 offset:50688
	ds_read_b64_tr_b16 v[150:151], v146 offset:54784
	ds_read_b64_tr_b16 v[154:155], v146 offset:58880
	ds_read_b64_tr_b16 v[156:157], v146 offset:62976
	ds_read_b64_tr_b16 v[158:159], v152 offset:17920
	ds_read_b64_tr_b16 v[160:161], v152 offset:22016
	ds_read_b64_tr_b16 v[226:227], v152 offset:26112
	ds_read_b64_tr_b16 v[228:229], v152 offset:30208
	s_waitcnt lgkmcnt(0)
	v_mfma_f32_32x32x16_bf16 v[66:81], v[142:145], v[148:151], v[66:81]
	v_mfma_f32_32x32x16_bf16 v[66:81], v[138:141], v[154:157], v[66:81]
	v_mfma_f32_32x32x16_bf16 v[66:81], v[130:133], v[158:161], v[66:81]
	v_mfma_f32_32x32x16_bf16 v[66:81], v[134:137], v[226:229], v[66:81]
	ds_read_b64_tr_b16 v[148:149], v146 offset:51200
	ds_read_b64_tr_b16 v[150:151], v146 offset:55296
	ds_read_b64_tr_b16 v[154:155], v146 offset:59392
	ds_read_b64_tr_b16 v[156:157], v146 offset:63488
	ds_read_b64_tr_b16 v[158:159], v152 offset:18432
	ds_read_b64_tr_b16 v[160:161], v152 offset:22528
	ds_read_b64_tr_b16 v[226:227], v152 offset:26624
	ds_read_b64_tr_b16 v[228:229], v152 offset:30720
	s_waitcnt lgkmcnt(0)
	v_mfma_f32_32x32x16_bf16 v[50:65], v[142:145], v[148:151], v[50:65]
	v_mfma_f32_32x32x16_bf16 v[50:65], v[138:141], v[154:157], v[50:65]
	v_mfma_f32_32x32x16_bf16 v[50:65], v[130:133], v[158:161], v[50:65]
	v_mfma_f32_32x32x16_bf16 v[50:65], v[134:137], v[226:229], v[50:65]
	ds_read_b64_tr_b16 v[148:149], v146 offset:51712
	ds_read_b64_tr_b16 v[150:151], v146 offset:55808
	ds_read_b64_tr_b16 v[154:155], v146 offset:59904
	ds_read_b64_tr_b16 v[156:157], v146 offset:64000
	ds_read_b64_tr_b16 v[158:159], v152 offset:18944
	ds_read_b64_tr_b16 v[160:161], v152 offset:23040
	ds_read_b64_tr_b16 v[226:227], v152 offset:27136
	ds_read_b64_tr_b16 v[228:229], v152 offset:31232
	s_waitcnt lgkmcnt(0)
	v_mfma_f32_32x32x16_bf16 v[34:49], v[142:145], v[148:151], v[34:49]
	v_mfma_f32_32x32x16_bf16 v[34:49], v[138:141], v[154:157], v[34:49]
	v_mfma_f32_32x32x16_bf16 v[34:49], v[130:133], v[158:161], v[34:49]
	v_mfma_f32_32x32x16_bf16 v[34:49], v[134:137], v[226:229], v[34:49]
	ds_read_b64_tr_b16 v[148:149], v146 offset:52224
	ds_read_b64_tr_b16 v[150:151], v146 offset:56320
	ds_read_b64_tr_b16 v[154:155], v146 offset:60416
	ds_read_b64_tr_b16 v[156:157], v146 offset:64512
	ds_read_b64_tr_b16 v[158:159], v152 offset:19456
	ds_read_b64_tr_b16 v[160:161], v152 offset:23552
	ds_read_b64_tr_b16 v[226:227], v152 offset:27648
	ds_read_b64_tr_b16 v[228:229], v152 offset:31744
	s_waitcnt lgkmcnt(0)
	v_mfma_f32_32x32x16_bf16 v[18:33], v[142:145], v[148:151], v[18:33]
	v_mfma_f32_32x32x16_bf16 v[18:33], v[138:141], v[154:157], v[18:33]
	v_mfma_f32_32x32x16_bf16 v[18:33], v[130:133], v[158:161], v[18:33]
	ds_read_b64_tr_b16 v[158:159], v146 offset:52736
	ds_read_b64_tr_b16 v[160:161], v146 offset:56832
	ds_read_b64_tr_b16 v[154:155], v146 offset:60928
	ds_read_b64_tr_b16 v[156:157], v146 offset:65024
	ds_read_b64_tr_b16 v[146:147], v152 offset:19968
	ds_read_b64_tr_b16 v[148:149], v152 offset:24064
	ds_read_b64_tr_b16 v[150:151], v152 offset:28160
	ds_read_b64_tr_b16 v[152:153], v152 offset:32256
	s_waitcnt lgkmcnt(0)
	v_mfma_f32_32x32x16_bf16 v[2:17], v[142:145], v[158:161], v[2:17]
	v_mfma_f32_32x32x16_bf16 v[2:17], v[138:141], v[154:157], v[2:17]
	v_mfma_f32_32x32x16_bf16 v[2:17], v[130:133], v[146:149], v[2:17]
	v_mfma_f32_32x32x16_bf16 v[18:33], v[134:137], v[226:229], v[18:33]
	v_mfma_f32_32x32x16_bf16 v[2:17], v[134:137], v[150:153], v[2:17]
	s_cbranch_scc0 .LBB0_1233
	s_cmp_ge_u32 s66, 0x80
	s_cbranch_scc1 .Lst1_b
	s_barrier
.Lst1_b:
	s_waitcnt vmcnt(6)
	v_lshl_add_u32 v202, s4, 14, v217
	s_waitcnt lgkmcnt(0)
	s_barrier
	v_add_u32_e32 v134, v202, v225
	ds_read_b128 v[130:133], v134
	ds_read_b128 v[146:149], v134 offset:8192
	s_waitcnt lgkmcnt(0)
	v_mfma_f32_32x32x16_bf16 v[130:145], v[130:133], v[190:193], 0
	v_add_u32_e32 v198, v202, v224
	ds_read_b128 v[194:197], v198
	ds_read_b128 v[198:201], v198 offset:8192
	v_cmp_gt_u32_e32 vcc, 32, v210
	v_mfma_f32_32x32x16_bf16 v[146:161], v[146:149], v[190:193], 0
	s_waitcnt lgkmcnt(0)
	v_mfma_f32_32x32x16_bf16 v[130:145], v[194:197], v[186:189], v[130:145]
	v_mfma_f32_32x32x16_bf16 v[146:161], v[198:201], v[186:189], v[146:161]
	v_add_u32_e32 v198, v202, v223
	ds_read_b128 v[194:197], v198
	ds_read_b128 v[198:201], v198 offset:8192
	s_waitcnt lgkmcnt(0)
	v_mfma_f32_32x32x16_bf16 v[130:145], v[194:197], v[182:185], v[130:145]
	v_mfma_f32_32x32x16_bf16 v[146:161], v[198:201], v[182:185], v[146:161]
	v_add_u32_e32 v198, v202, v222
	ds_read_b128 v[194:197], v198
	ds_read_b128 v[198:201], v198 offset:8192
	s_waitcnt lgkmcnt(0)
	v_mfma_f32_32x32x16_bf16 v[130:145], v[194:197], v[178:181], v[130:145]
	v_mfma_f32_32x32x16_bf16 v[146:161], v[198:201], v[178:181], v[146:161]
	v_add_u32_e32 v198, v202, v221
	ds_read_b128 v[194:197], v198
	ds_read_b128 v[198:201], v198 offset:8192
	s_waitcnt lgkmcnt(0)
	v_mfma_f32_32x32x16_bf16 v[130:145], v[194:197], v[174:177], v[130:145]
	v_mfma_f32_32x32x16_bf16 v[146:161], v[198:201], v[174:177], v[146:161]
	v_add_u32_e32 v198, v202, v220
	ds_read_b128 v[194:197], v198
	ds_read_b128 v[198:201], v198 offset:8192
	s_waitcnt lgkmcnt(0)
	v_mfma_f32_32x32x16_bf16 v[130:145], v[194:197], v[170:173], v[130:145]
	v_mfma_f32_32x32x16_bf16 v[146:161], v[198:201], v[170:173], v[146:161]
	v_add_u32_e32 v198, v202, v219
	ds_read_b128 v[194:197], v198
	ds_read_b128 v[198:201], v198 offset:8192
	s_waitcnt lgkmcnt(0)
	v_mfma_f32_32x32x16_bf16 v[130:145], v[194:197], v[166:169], v[130:145]
	v_mfma_f32_32x32x16_bf16 v[146:161], v[198:201], v[166:169], v[146:161]
	v_add_u32_e32 v198, v202, v218
	ds_read_b128 v[194:197], v198
	ds_read_b128 v[198:201], v198 offset:8192
	s_waitcnt lgkmcnt(0)
	v_mfma_f32_32x32x16_bf16 v[130:145], v[194:197], v[162:165], v[130:145]
	v_add_u32_e32 v195, v217, v224
	v_mfma_f32_32x32x16_bf16 v[146:161], v[198:201], v[162:165], v[146:161]
	s_nop 9
	v_fmamk_f32 v130, v130, 0x3e0293ee, v215
	v_exp_f32_e32 v130, v130
	v_fmamk_f32 v131, v131, 0x3e0293ee, v215
	v_exp_f32_e32 v131, v131
	v_fmamk_f32 v132, v132, 0x3e0293ee, v215
	v_exp_f32_e32 v132, v132
	v_fmamk_f32 v133, v133, 0x3e0293ee, v215
	v_exp_f32_e32 v133, v133
	v_fmamk_f32 v134, v134, 0x3e0293ee, v215
	v_exp_f32_e32 v134, v134
	v_fmamk_f32 v135, v135, 0x3e0293ee, v215
	v_add_f32_e32 v194, 0, v130
	v_exp_f32_e32 v135, v135
	v_fmamk_f32 v136, v136, 0x3e0293ee, v215
	v_add_f32_e32 v194, v131, v194
	v_exp_f32_e32 v136, v136
	v_fmamk_f32 v137, v137, 0x3e0293ee, v215
	v_add_f32_e32 v194, v132, v194
	v_exp_f32_e32 v137, v137
	v_fmamk_f32 v138, v138, 0x3e0293ee, v215
	v_add_f32_e32 v194, v133, v194
	v_exp_f32_e32 v138, v138
	v_fmamk_f32 v139, v139, 0x3e0293ee, v215
	v_add_f32_e32 v194, v134, v194
	v_exp_f32_e32 v139, v139
	v_fmamk_f32 v140, v140, 0x3e0293ee, v215
	v_add_f32_e32 v194, v135, v194
	v_exp_f32_e32 v140, v140
	v_fmamk_f32 v141, v141, 0x3e0293ee, v215
	v_add_f32_e32 v194, v136, v194
	v_exp_f32_e32 v141, v141
	v_fmamk_f32 v142, v142, 0x3e0293ee, v215
	v_add_f32_e32 v194, v137, v194
	v_exp_f32_e32 v142, v142
	v_fmamk_f32 v143, v143, 0x3e0293ee, v215
	v_add_f32_e32 v194, v138, v194
	v_exp_f32_e32 v143, v143
	v_fmamk_f32 v144, v144, 0x3e0293ee, v215
	v_add_f32_e32 v194, v139, v194
	v_exp_f32_e32 v144, v144
	v_fmamk_f32 v145, v145, 0x3e0293ee, v215
	v_add_f32_e32 v194, v140, v194
	v_fmamk_f32 v146, v146, 0x3e0293ee, v215
	v_exp_f32_e32 v145, v145
	v_add_f32_e32 v194, v141, v194
	v_exp_f32_e32 v146, v146
	v_fmamk_f32 v147, v147, 0x3e0293ee, v215
	v_add_f32_e32 v194, v142, v194
	v_exp_f32_e32 v147, v147
	v_fmamk_f32 v148, v148, 0x3e0293ee, v215
	v_add_f32_e32 v194, v143, v194
	v_exp_f32_e32 v148, v148
	v_fmamk_f32 v149, v149, 0x3e0293ee, v215
	v_add_f32_e32 v194, v144, v194
	v_exp_f32_e32 v149, v149
	v_fmamk_f32 v150, v150, 0x3e0293ee, v215
	v_add_f32_e32 v194, v145, v194
	v_exp_f32_e32 v150, v150
	v_fmamk_f32 v151, v151, 0x3e0293ee, v215
	v_add_f32_e32 v194, v146, v194
	v_exp_f32_e32 v151, v151
	v_fmamk_f32 v152, v152, 0x3e0293ee, v215
	v_add_f32_e32 v194, v147, v194
	v_exp_f32_e32 v152, v152
	v_fmamk_f32 v153, v153, 0x3e0293ee, v215
	v_add_f32_e32 v194, v148, v194
	v_exp_f32_e32 v153, v153
	v_fmamk_f32 v154, v154, 0x3e0293ee, v215
	v_add_f32_e32 v194, v149, v194
	v_exp_f32_e32 v154, v154
	v_fmamk_f32 v155, v155, 0x3e0293ee, v215
	v_add_f32_e32 v194, v150, v194
	v_exp_f32_e32 v155, v155
	v_fmamk_f32 v156, v156, 0x3e0293ee, v215
	v_add_f32_e32 v194, v151, v194
	v_exp_f32_e32 v156, v156
	v_fmamk_f32 v157, v157, 0x3e0293ee, v215
	v_add_f32_e32 v194, v152, v194
	v_exp_f32_e32 v157, v157
	v_fmamk_f32 v158, v158, 0x3e0293ee, v215
	v_add_f32_e32 v194, v153, v194
	v_cvt_pk_bf16_f32 v130, v130, v131
	v_cvt_pk_bf16_f32 v131, v132, v133
	v_cvt_pk_bf16_f32 v132, v134, v135
	v_cvt_pk_bf16_f32 v133, v136, v137
	v_exp_f32_e32 v158, v158
	v_fmamk_f32 v159, v159, 0x3e0293ee, v215
	v_add_f32_e32 v194, v154, v194
	v_permlane32_swap_b32_e32 v130, v132
	v_permlane32_swap_b32_e32 v131, v133
	v_exp_f32_e32 v159, v159
	v_add_f32_e32 v194, v155, v194
	v_add_f32_e32 v194, v156, v194
	v_add_f32_e32 v194, v157, v194
	v_add_f32_e32 v194, v158, v194
	v_cvt_pk_bf16_f32 v134, v138, v139
	v_cvt_pk_bf16_f32 v138, v146, v147
	v_lshl_add_u32 v147, s4, 15, v216
	v_add_f32_e32 v194, v159, v194
	v_cvt_pk_bf16_f32 v135, v140, v141
	v_cvt_pk_bf16_f32 v136, v142, v143
	v_cvt_pk_bf16_f32 v137, v144, v145
	v_cvt_pk_bf16_f32 v139, v148, v149
	v_cvt_pk_bf16_f32 v140, v150, v151
	v_cvt_pk_bf16_f32 v141, v152, v153
	v_cvt_pk_bf16_f32 v142, v154, v155
	v_cvt_pk_bf16_f32 v143, v156, v157
	v_cvt_pk_bf16_f32 v144, v158, v159
	v_add_u32_e32 v146, 0xc000, v147
	ds_read_b64_tr_b16 v[148:149], v147 offset:49152
	ds_read_b64_tr_b16 v[150:151], v147 offset:53248
	ds_read_b64_tr_b16 v[152:153], v147 offset:57344
	ds_read_b64_tr_b16 v[154:155], v147 offset:61440
	ds_read_b64_tr_b16 v[156:157], v146 offset:16384
	ds_read_b64_tr_b16 v[158:159], v146 offset:20480
	ds_read_b64_tr_b16 v[198:199], v146 offset:24576
	ds_read_b64_tr_b16 v[200:201], v146 offset:28672
	s_waitcnt lgkmcnt(0)
	v_mfma_f32_32x32x16_bf16 v[114:129], v[130:133], v[148:151], v[114:129]
	v_permlane32_swap_b32_e32 v134, v136
	v_permlane32_swap_b32_e32 v135, v137
	v_permlane32_swap_b32_e32 v138, v140
	v_permlane32_swap_b32_e32 v139, v141
	v_mfma_f32_32x32x16_bf16 v[114:129], v[134:137], v[152:155], v[114:129]
	v_fmamk_f32 v160, v160, 0x3e0293ee, v215
	v_fmamk_f32 v161, v161, 0x3e0293ee, v215
	v_exp_f32_e32 v160, v160
	v_exp_f32_e32 v161, v161
	v_permlane32_swap_b32_e32 v142, v144
	v_add_f32_e32 v194, v160, v194
	v_mfma_f32_32x32x16_bf16 v[114:129], v[138:141], v[156:159], v[114:129]
	v_cvt_pk_bf16_f32 v145, v160, v161
	s_nop 1
	v_permlane32_swap_b32_e32 v143, v145
	v_add_f32_e32 v194, v161, v194
	v_mov_b32_e32 v196, v194
	s_nop 1
	v_permlane32_swap_b32_e32 v194, v196
	v_mfma_f32_32x32x16_bf16 v[114:129], v[142:145], v[198:201], v[114:129]
	ds_read_b64_tr_b16 v[148:149], v147 offset:49664
	ds_read_b64_tr_b16 v[150:151], v147 offset:53760
	ds_read_b64_tr_b16 v[152:153], v147 offset:57856
	ds_read_b64_tr_b16 v[154:155], v147 offset:61952
	ds_read_b64_tr_b16 v[156:157], v146 offset:16896
	ds_read_b64_tr_b16 v[158:159], v146 offset:20992
	ds_read_b64_tr_b16 v[198:199], v146 offset:25088
	ds_read_b64_tr_b16 v[200:201], v146 offset:29184
	s_waitcnt lgkmcnt(0)
	v_mfma_f32_32x32x16_bf16 v[98:113], v[130:133], v[148:151], v[98:113]
	v_mfma_f32_32x32x16_bf16 v[98:113], v[134:137], v[152:155], v[98:113]
	v_mfma_f32_32x32x16_bf16 v[98:113], v[138:141], v[156:159], v[98:113]
	v_mfma_f32_32x32x16_bf16 v[98:113], v[142:145], v[198:201], v[98:113]
	ds_read_b64_tr_b16 v[148:149], v147 offset:50176
	ds_read_b64_tr_b16 v[150:151], v147 offset:54272
	ds_read_b64_tr_b16 v[152:153], v147 offset:58368
	ds_read_b64_tr_b16 v[154:155], v147 offset:62464
	ds_read_b64_tr_b16 v[156:157], v146 offset:17408
	ds_read_b64_tr_b16 v[158:159], v146 offset:21504
	ds_read_b64_tr_b16 v[198:199], v146 offset:25600
	ds_read_b64_tr_b16 v[200:201], v146 offset:29696
	s_waitcnt lgkmcnt(0)
	v_mfma_f32_32x32x16_bf16 v[82:97], v[130:133], v[148:151], v[82:97]
	v_mfma_f32_32x32x16_bf16 v[82:97], v[134:137], v[152:155], v[82:97]
	v_mfma_f32_32x32x16_bf16 v[82:97], v[138:141], v[156:159], v[82:97]
	v_mfma_f32_32x32x16_bf16 v[82:97], v[142:145], v[198:201], v[82:97]
	ds_read_b64_tr_b16 v[148:149], v147 offset:50688
	ds_read_b64_tr_b16 v[150:151], v147 offset:54784
	ds_read_b64_tr_b16 v[152:153], v147 offset:58880
	ds_read_b64_tr_b16 v[154:155], v147 offset:62976
	ds_read_b64_tr_b16 v[156:157], v146 offset:17920
	ds_read_b64_tr_b16 v[158:159], v146 offset:22016
	ds_read_b64_tr_b16 v[198:199], v146 offset:26112
	ds_read_b64_tr_b16 v[200:201], v146 offset:30208
	s_waitcnt lgkmcnt(0)
	v_mfma_f32_32x32x16_bf16 v[66:81], v[130:133], v[148:151], v[66:81]
	v_mfma_f32_32x32x16_bf16 v[66:81], v[134:137], v[152:155], v[66:81]
	v_mfma_f32_32x32x16_bf16 v[66:81], v[138:141], v[156:159], v[66:81]
	v_mfma_f32_32x32x16_bf16 v[66:81], v[142:145], v[198:201], v[66:81]
	ds_read_b64_tr_b16 v[148:149], v147 offset:51200
	ds_read_b64_tr_b16 v[150:151], v147 offset:55296
	ds_read_b64_tr_b16 v[152:153], v147 offset:59392
	ds_read_b64_tr_b16 v[154:155], v147 offset:63488
	ds_read_b64_tr_b16 v[156:157], v146 offset:18432
	ds_read_b64_tr_b16 v[158:159], v146 offset:22528
	ds_read_b64_tr_b16 v[198:199], v146 offset:26624
	ds_read_b64_tr_b16 v[200:201], v146 offset:30720
	s_waitcnt lgkmcnt(0)
	v_mfma_f32_32x32x16_bf16 v[50:65], v[130:133], v[148:151], v[50:65]
	v_mfma_f32_32x32x16_bf16 v[50:65], v[134:137], v[152:155], v[50:65]
	v_mfma_f32_32x32x16_bf16 v[50:65], v[138:141], v[156:159], v[50:65]
	v_mfma_f32_32x32x16_bf16 v[50:65], v[142:145], v[198:201], v[50:65]
	ds_read_b64_tr_b16 v[148:149], v147 offset:51712
	ds_read_b64_tr_b16 v[150:151], v147 offset:55808
	ds_read_b64_tr_b16 v[152:153], v147 offset:59904
	ds_read_b64_tr_b16 v[154:155], v147 offset:64000
	ds_read_b64_tr_b16 v[156:157], v146 offset:18944
	ds_read_b64_tr_b16 v[158:159], v146 offset:23040
	ds_read_b64_tr_b16 v[198:199], v146 offset:27136
	ds_read_b64_tr_b16 v[200:201], v146 offset:31232
	s_waitcnt lgkmcnt(0)
	v_mfma_f32_32x32x16_bf16 v[34:49], v[130:133], v[148:151], v[34:49]
	v_mfma_f32_32x32x16_bf16 v[34:49], v[134:137], v[152:155], v[34:49]
	v_mfma_f32_32x32x16_bf16 v[34:49], v[138:141], v[156:159], v[34:49]
	v_mfma_f32_32x32x16_bf16 v[34:49], v[142:145], v[198:201], v[34:49]
	ds_read_b64_tr_b16 v[148:149], v147 offset:52224
	ds_read_b64_tr_b16 v[150:151], v147 offset:56320
	ds_read_b64_tr_b16 v[152:153], v147 offset:60416
	ds_read_b64_tr_b16 v[154:155], v147 offset:64512
	ds_read_b64_tr_b16 v[156:157], v146 offset:19456
	ds_read_b64_tr_b16 v[158:159], v146 offset:23552
	ds_read_b64_tr_b16 v[198:199], v146 offset:27648
	ds_read_b64_tr_b16 v[200:201], v146 offset:31744
	s_waitcnt lgkmcnt(0)
	v_mfma_f32_32x32x16_bf16 v[18:33], v[130:133], v[148:151], v[18:33]
	v_mfma_f32_32x32x16_bf16 v[18:33], v[134:137], v[152:155], v[18:33]
	v_mfma_f32_32x32x16_bf16 v[18:33], v[138:141], v[156:159], v[18:33]
	v_mfma_f32_32x32x16_bf16 v[18:33], v[142:145], v[198:201], v[18:33]
	ds_read_b64_tr_b16 v[148:149], v147 offset:52736
	ds_read_b64_tr_b16 v[150:151], v147 offset:56832
	ds_read_b64_tr_b16 v[152:153], v147 offset:60928
	ds_read_b64_tr_b16 v[154:155], v147 offset:65024
	ds_read_b64_tr_b16 v[156:157], v146 offset:19968
	ds_read_b64_tr_b16 v[158:159], v146 offset:24064
	ds_read_b64_tr_b16 v[198:199], v146 offset:28160
	ds_read_b64_tr_b16 v[200:201], v146 offset:32256
	s_waitcnt vmcnt(0)
	s_waitcnt lgkmcnt(0)
	s_barrier
	s_waitcnt lgkmcnt(0)
	v_mfma_f32_32x32x16_bf16 v[2:17], v[130:133], v[148:151], v[2:17]
	v_mfma_f32_32x32x16_bf16 v[2:17], v[134:137], v[152:155], v[2:17]
	v_add_u32_e32 v134, v217, v225
	ds_read_b128 v[130:133], v134 offset:32768
	ds_read_b128 v[134:137], v134 offset:40960
	v_mfma_f32_32x32x16_bf16 v[2:17], v[138:141], v[156:159], v[2:17]
	v_mfma_f32_32x32x16_bf16 v[2:17], v[142:145], v[198:201], v[2:17]
	s_waitcnt lgkmcnt(0)
	v_mfma_f32_32x32x16_bf16 v[146:161], v[130:133], v[190:193], 0
	v_mfma_f32_32x32x16_bf16 v[130:145], v[134:137], v[190:193], 0
	ds_read_b128 v[190:193], v195 offset:32768
	ds_read_b128 v[198:201], v195 offset:40960
	s_waitcnt lgkmcnt(0)
	v_mfma_f32_32x32x16_bf16 v[130:145], v[198:201], v[186:189], v[130:145]
	v_mfma_f32_32x32x16_bf16 v[146:161], v[190:193], v[186:189], v[146:161]
	v_add_u32_e32 v190, v217, v223
	ds_read_b128 v[186:189], v190 offset:32768
	ds_read_b128 v[190:193], v190 offset:40960
	s_waitcnt lgkmcnt(0)
	v_mfma_f32_32x32x16_bf16 v[130:145], v[190:193], v[182:185], v[130:145]
	v_mfma_f32_32x32x16_bf16 v[146:161], v[186:189], v[182:185], v[146:161]
	v_add_u32_e32 v186, v217, v222
	ds_read_b128 v[182:185], v186 offset:32768
	ds_read_b128 v[186:189], v186 offset:40960
	s_waitcnt lgkmcnt(0)
	v_mfma_f32_32x32x16_bf16 v[130:145], v[186:189], v[178:181], v[130:145]
	v_mfma_f32_32x32x16_bf16 v[146:161], v[182:185], v[178:181], v[146:161]
	v_add_u32_e32 v182, v217, v221
	ds_read_b128 v[178:181], v182 offset:32768
	ds_read_b128 v[182:185], v182 offset:40960
	s_waitcnt lgkmcnt(0)
	v_mfma_f32_32x32x16_bf16 v[130:145], v[182:185], v[174:177], v[130:145]
	v_mfma_f32_32x32x16_bf16 v[146:161], v[178:181], v[174:177], v[146:161]
	v_add_u32_e32 v178, v217, v220
	ds_read_b128 v[174:177], v178 offset:32768
	ds_read_b128 v[178:181], v178 offset:40960
	s_waitcnt lgkmcnt(0)
	v_mfma_f32_32x32x16_bf16 v[130:145], v[178:181], v[170:173], v[130:145]
	v_mfma_f32_32x32x16_bf16 v[146:161], v[174:177], v[170:173], v[146:161]
	v_add_u32_e32 v174, v217, v219
	ds_read_b128 v[170:173], v174 offset:32768
	ds_read_b128 v[174:177], v174 offset:40960
	s_waitcnt lgkmcnt(0)
	v_mfma_f32_32x32x16_bf16 v[130:145], v[174:177], v[166:169], v[130:145]
	v_mfma_f32_32x32x16_bf16 v[146:161], v[170:173], v[166:169], v[146:161]
	v_add_u32_e32 v170, v217, v218
	ds_read_b128 v[166:169], v170 offset:32768
	ds_read_b128 v[170:173], v170 offset:40960
	s_waitcnt lgkmcnt(0)
	v_mfma_f32_32x32x16_bf16 v[130:145], v[170:173], v[162:165], v[130:145]
	v_mfma_f32_32x32x16_bf16 v[146:161], v[166:169], v[162:165], v[146:161]
	s_nop 10
	v_fmamk_f32 v138, v138, 0x3e0293ee, v215
	v_fmamk_f32 v139, v139, 0x3e0293ee, v215
	v_fmamk_f32 v140, v140, 0x3e0293ee, v215
	v_fmamk_f32 v141, v141, 0x3e0293ee, v215
	v_fmamk_f32 v142, v142, 0x3e0293ee, v215
	v_exp_f32_e32 v162, v138
	v_fmamk_f32 v130, v130, 0x3e0293ee, v215
	v_fmamk_f32 v138, v155, 0x3e0293ee, v215
	v_exp_f32_e32 v155, v139
	v_fmamk_f32 v139, v156, 0x3e0293ee, v215
	v_exp_f32_e32 v156, v140
	v_fmamk_f32 v140, v157, 0x3e0293ee, v215
	v_exp_f32_e32 v157, v141
	v_fmamk_f32 v141, v158, 0x3e0293ee, v215
	v_exp_f32_e32 v158, v142
	v_fmamk_f32 v142, v159, 0x3e0293ee, v215
	v_fmamk_f32 v146, v146, 0x3e0293ee, v215
	v_exp_f32_e32 v159, v142
	v_fmamk_f32 v142, v143, 0x3e0293ee, v215
	v_exp_f32_e32 v146, v146
	v_fmamk_f32 v147, v147, 0x3e0293ee, v215
	v_exp_f32_e32 v163, v142
	v_fmamk_f32 v142, v160, 0x3e0293ee, v215
	v_exp_f32_e32 v147, v147
	v_fmamk_f32 v148, v148, 0x3e0293ee, v215
	v_exp_f32_e32 v160, v142
	v_fmamk_f32 v142, v144, 0x3e0293ee, v215
	v_exp_f32_e32 v148, v148
	v_fmamk_f32 v149, v149, 0x3e0293ee, v215
	v_exp_f32_e32 v164, v142
	v_fmamk_f32 v142, v161, 0x3e0293ee, v215
	v_exp_f32_e32 v149, v149
	v_fmamk_f32 v150, v150, 0x3e0293ee, v215
	v_exp_f32_e32 v161, v142
	v_fmamk_f32 v142, v145, 0x3e0293ee, v215
	v_exp_f32_e32 v150, v150
	v_fmamk_f32 v151, v151, 0x3e0293ee, v215
	v_exp_f32_e32 v165, v142
	v_add_f32_e32 v142, 0, v146
	v_exp_f32_e32 v151, v151
	v_fmamk_f32 v152, v152, 0x3e0293ee, v215
	v_add_f32_e32 v142, v147, v142
	v_exp_f32_e32 v152, v152
	v_fmamk_f32 v153, v153, 0x3e0293ee, v215
	v_add_f32_e32 v142, v148, v142
	v_exp_f32_e32 v153, v153
	v_fmamk_f32 v154, v154, 0x3e0293ee, v215
	v_add_f32_e32 v142, v149, v142
	v_exp_f32_e32 v154, v154
	v_add_f32_e32 v142, v150, v142
	v_exp_f32_e32 v138, v138
	v_add_f32_e32 v142, v151, v142
	v_exp_f32_e32 v139, v139
	v_add_f32_e32 v142, v152, v142
	v_exp_f32_e32 v140, v140
	v_add_f32_e32 v142, v153, v142
	v_exp_f32_e32 v141, v141
	v_add_f32_e32 v142, v154, v142
	v_add_f32_e32 v142, v138, v142
	v_add_f32_e32 v142, v139, v142
	v_add_f32_e32 v142, v140, v142
	v_exp_f32_e32 v130, v130
	v_fmamk_f32 v131, v131, 0x3e0293ee, v215
	v_add_f32_e32 v142, v141, v142
	v_exp_f32_e32 v131, v131
	v_fmamk_f32 v132, v132, 0x3e0293ee, v215
	v_add_f32_e32 v142, v159, v142
	v_exp_f32_e32 v132, v132
	v_fmamk_f32 v133, v133, 0x3e0293ee, v215
	v_add_f32_e32 v142, v160, v142
	v_exp_f32_e32 v133, v133
	v_fmamk_f32 v134, v134, 0x3e0293ee, v215
	v_add_f32_e32 v142, v161, v142
	v_exp_f32_e32 v134, v134
	v_fmamk_f32 v135, v135, 0x3e0293ee, v215
	v_add_f32_e32 v142, v130, v142
	v_exp_f32_e32 v135, v135
	v_fmamk_f32 v136, v136, 0x3e0293ee, v215
	v_add_f32_e32 v142, v131, v142
	v_exp_f32_e32 v136, v136
	v_fmamk_f32 v137, v137, 0x3e0293ee, v215
	v_add_f32_e32 v142, v132, v142
	v_exp_f32_e32 v137, v137
	v_add_f32_e32 v142, v133, v142
	v_add_f32_e32 v142, v134, v142
	v_add_f32_e32 v142, v135, v142
	v_add_f32_e32 v142, v136, v142
	v_add_f32_e32 v142, v137, v142
	v_add_f32_e32 v142, v162, v142
	v_add_f32_e32 v142, v155, v142
	v_add_f32_e32 v142, v156, v142
	v_add_f32_e32 v142, v157, v142
	v_add_f32_e32 v142, v158, v142
	v_add_f32_e32 v142, v163, v142
	v_add_f32_e32 v142, v164, v142
	v_add_f32_e32 v195, v165, v142
	v_cvt_pk_bf16_f32 v142, v146, v147
	v_cvt_pk_bf16_f32 v143, v148, v149
	v_cvt_pk_bf16_f32 v144, v150, v151
	v_cvt_pk_bf16_f32 v145, v152, v153
	v_add_u32_e32 v146, 0x1c000, v216
	v_add_u32_e32 v148, 0x1d000, v216
	v_permlane32_swap_b32_e32 v142, v144
	v_permlane32_swap_b32_e32 v143, v145
	ds_read_b64_tr_b16 v[146:147], v146
	ds_read_b64_tr_b16 v[148:149], v148
	v_add_u32_e32 v150, 0x1e000, v216
	v_add_u32_e32 v152, 0x1f000, v216
	ds_read_b64_tr_b16 v[150:151], v150
	ds_read_b64_tr_b16 v[152:153], v152
	s_waitcnt lgkmcnt(0)
	v_mfma_f32_32x32x16_bf16 v[114:129], v[142:145], v[146:149], v[114:129]
	v_cvt_pk_bf16_f32 v138, v154, v138
	v_cvt_pk_bf16_f32 v139, v139, v140
	v_cvt_pk_bf16_f32 v140, v141, v159
	v_cvt_pk_bf16_f32 v141, v160, v161
	s_nop 0
	v_permlane32_swap_b32_e32 v138, v140
	v_permlane32_swap_b32_e32 v139, v141
	v_add_u32_e32 v146, 0x1c200, v216
	v_add_u32_e32 v148, 0x1d200, v216
	ds_read_b64_tr_b16 v[146:147], v146
	ds_read_b64_tr_b16 v[148:149], v148
	v_mfma_f32_32x32x16_bf16 v[114:129], v[138:141], v[150:153], v[114:129]
	v_add_u32_e32 v150, 0x1e200, v216
	v_add_u32_e32 v152, 0x1f200, v216
	ds_read_b64_tr_b16 v[150:151], v150
	ds_read_b64_tr_b16 v[152:153], v152
	v_cvt_pk_bf16_f32 v130, v130, v131
	v_cvt_pk_bf16_f32 v131, v132, v133
	v_cvt_pk_bf16_f32 v132, v134, v135
	s_waitcnt lgkmcnt(0)
	v_mfma_f32_32x32x16_bf16 v[98:113], v[142:145], v[146:149], v[98:113]
	v_cvt_pk_bf16_f32 v133, v136, v137
	v_cvt_pk_bf16_f32 v135, v156, v157
	v_add_u32_e32 v154, 0x20000, v216
	v_add_u32_e32 v156, 0x21000, v216
	v_permlane32_swap_b32_e32 v130, v132
	v_permlane32_swap_b32_e32 v131, v133
	v_cvt_pk_bf16_f32 v134, v162, v155
	ds_read_b64_tr_b16 v[154:155], v154
	ds_read_b64_tr_b16 v[156:157], v156
	v_add_u32_e32 v146, 0x1c400, v216
	v_add_u32_e32 v148, 0x1d400, v216
	ds_read_b64_tr_b16 v[146:147], v146
	ds_read_b64_tr_b16 v[148:149], v148
	v_cvt_pk_bf16_f32 v136, v158, v163
	v_add_u32_e32 v158, 0x22000, v216
	v_add_u32_e32 v160, 0x23000, v216
	ds_read_b64_tr_b16 v[158:159], v158
	ds_read_b64_tr_b16 v[160:161], v160
	s_waitcnt lgkmcnt(0)
	v_mfma_f32_32x32x16_bf16 v[114:129], v[130:133], v[154:157], v[114:129]
	v_cvt_pk_bf16_f32 v137, v164, v165
	v_permlane32_swap_b32_e32 v134, v136
	s_nop 0
	v_permlane32_swap_b32_e32 v135, v137
	v_add_u32_e32 v154, 0x20200, v216
	v_add_u32_e32 v156, 0x21200, v216
	v_mfma_f32_32x32x16_bf16 v[98:113], v[138:141], v[150:153], v[98:113]
	v_add_u32_e32 v150, 0x1e400, v216
	v_add_u32_e32 v152, 0x1f400, v216
	ds_read_b64_tr_b16 v[150:151], v150
	ds_read_b64_tr_b16 v[152:153], v152
	ds_read_b64_tr_b16 v[154:155], v154
	ds_read_b64_tr_b16 v[156:157], v156
	v_mov_b32_e32 v197, v195
	v_mfma_f32_32x32x16_bf16 v[82:97], v[142:145], v[146:149], v[82:97]
	v_add_u32_e32 v146, 0x1c600, v216
	v_add_u32_e32 v148, 0x1d600, v216
	ds_read_b64_tr_b16 v[146:147], v146
	ds_read_b64_tr_b16 v[148:149], v148
	v_permlane32_swap_b32_e32 v195, v197
	v_mfma_f32_32x32x16_bf16 v[114:129], v[134:137], v[158:161], v[114:129]
	v_add_u32_e32 v158, 0x22200, v216
	v_add_u32_e32 v160, 0x23200, v216
	ds_read_b64_tr_b16 v[158:159], v158
	ds_read_b64_tr_b16 v[160:161], v160
	s_waitcnt lgkmcnt(0)
	v_mfma_f32_32x32x16_bf16 v[98:113], v[130:133], v[154:157], v[98:113]
	v_add_u32_e32 v154, 0x20400, v216
	v_add_u32_e32 v156, 0x21400, v216
	ds_read_b64_tr_b16 v[154:155], v154
	ds_read_b64_tr_b16 v[156:157], v156
	v_mfma_f32_32x32x16_bf16 v[82:97], v[138:141], v[150:153], v[82:97]
	v_add_u32_e32 v150, 0x1e600, v216
	v_add_u32_e32 v152, 0x1f600, v216
	ds_read_b64_tr_b16 v[150:151], v150
	ds_read_b64_tr_b16 v[152:153], v152
	v_mfma_f32_32x32x16_bf16 v[66:81], v[142:145], v[146:149], v[66:81]
	v_add_u32_e32 v146, 0x1c800, v216
	v_add_u32_e32 v148, 0x1d800, v216
	ds_read_b64_tr_b16 v[146:147], v146
	ds_read_b64_tr_b16 v[148:149], v148
	v_mfma_f32_32x32x16_bf16 v[98:113], v[134:137], v[158:161], v[98:113]
	v_add_u32_e32 v158, 0x22400, v216
	v_add_u32_e32 v160, 0x23400, v216
	ds_read_b64_tr_b16 v[158:159], v158
	ds_read_b64_tr_b16 v[160:161], v160
	s_waitcnt lgkmcnt(0)
	v_mfma_f32_32x32x16_bf16 v[82:97], v[130:133], v[154:157], v[82:97]
	v_add_u32_e32 v154, 0x20600, v216
	v_add_u32_e32 v156, 0x21600, v216
	ds_read_b64_tr_b16 v[154:155], v154
	ds_read_b64_tr_b16 v[156:157], v156
	v_mfma_f32_32x32x16_bf16 v[66:81], v[138:141], v[150:153], v[66:81]
	v_add_u32_e32 v150, 0x1e800, v216
	v_add_u32_e32 v152, 0x1f800, v216
	ds_read_b64_tr_b16 v[150:151], v150
	ds_read_b64_tr_b16 v[152:153], v152
	v_mfma_f32_32x32x16_bf16 v[50:65], v[142:145], v[146:149], v[50:65]
	v_add_u32_e32 v146, 0x1ca00, v216
	v_add_u32_e32 v148, 0x1da00, v216
	ds_read_b64_tr_b16 v[146:147], v146
	ds_read_b64_tr_b16 v[148:149], v148
	v_mfma_f32_32x32x16_bf16 v[82:97], v[134:137], v[158:161], v[82:97]
	v_add_u32_e32 v158, 0x22600, v216
	v_add_u32_e32 v160, 0x23600, v216
	ds_read_b64_tr_b16 v[158:159], v158
	ds_read_b64_tr_b16 v[160:161], v160
	s_waitcnt lgkmcnt(0)
	v_mfma_f32_32x32x16_bf16 v[66:81], v[130:133], v[154:157], v[66:81]
	v_add_u32_e32 v154, 0x20800, v216
	v_add_u32_e32 v156, 0x21800, v216
	ds_read_b64_tr_b16 v[154:155], v154
	ds_read_b64_tr_b16 v[156:157], v156
	v_mfma_f32_32x32x16_bf16 v[50:65], v[138:141], v[150:153], v[50:65]
	v_add_u32_e32 v150, 0x1ea00, v216
	v_add_u32_e32 v152, 0x1fa00, v216
	ds_read_b64_tr_b16 v[150:151], v150
	ds_read_b64_tr_b16 v[152:153], v152
	v_mfma_f32_32x32x16_bf16 v[34:49], v[142:145], v[146:149], v[34:49]
	v_add_u32_e32 v146, 0x1cc00, v216
	v_add_u32_e32 v148, 0x1dc00, v216
	ds_read_b64_tr_b16 v[146:147], v146
	ds_read_b64_tr_b16 v[148:149], v148
	v_mfma_f32_32x32x16_bf16 v[66:81], v[134:137], v[158:161], v[66:81]
	v_add_u32_e32 v158, 0x22800, v216
	v_add_u32_e32 v160, 0x23800, v216
	ds_read_b64_tr_b16 v[158:159], v158
	ds_read_b64_tr_b16 v[160:161], v160
	s_waitcnt lgkmcnt(0)
	v_mfma_f32_32x32x16_bf16 v[50:65], v[130:133], v[154:157], v[50:65]
	v_add_u32_e32 v154, 0x20a00, v216
	v_add_u32_e32 v156, 0x21a00, v216
	ds_read_b64_tr_b16 v[154:155], v154
	ds_read_b64_tr_b16 v[156:157], v156
	v_mfma_f32_32x32x16_bf16 v[34:49], v[138:141], v[150:153], v[34:49]
	v_add_u32_e32 v150, 0x1ec00, v216
	v_add_u32_e32 v152, 0x1fc00, v216
	ds_read_b64_tr_b16 v[150:151], v150
	ds_read_b64_tr_b16 v[152:153], v152
	v_mfma_f32_32x32x16_bf16 v[18:33], v[142:145], v[146:149], v[18:33]
	v_add_u32_e32 v146, 0x1ce00, v216
	v_add_u32_e32 v148, 0x1de00, v216
	ds_read_b64_tr_b16 v[146:147], v146
	ds_read_b64_tr_b16 v[148:149], v148
	v_mfma_f32_32x32x16_bf16 v[50:65], v[134:137], v[158:161], v[50:65]
	v_add_u32_e32 v158, 0x22a00, v216
	v_add_u32_e32 v160, 0x23a00, v216
	ds_read_b64_tr_b16 v[158:159], v158
	ds_read_b64_tr_b16 v[160:161], v160
	s_waitcnt lgkmcnt(0)
	v_mfma_f32_32x32x16_bf16 v[34:49], v[130:133], v[154:157], v[34:49]
	v_add_u32_e32 v154, 0x20c00, v216
	v_add_u32_e32 v156, 0x21c00, v216
	ds_read_b64_tr_b16 v[154:155], v154
	ds_read_b64_tr_b16 v[156:157], v156
	v_mfma_f32_32x32x16_bf16 v[18:33], v[138:141], v[150:153], v[18:33]
	v_add_u32_e32 v150, 0x1ee00, v216
	v_add_u32_e32 v152, 0x1fe00, v216
	ds_read_b64_tr_b16 v[150:151], v150
	ds_read_b64_tr_b16 v[152:153], v152
	v_mfma_f32_32x32x16_bf16 v[2:17], v[142:145], v[146:149], v[2:17]
	v_mfma_f32_32x32x16_bf16 v[34:49], v[134:137], v[158:161], v[34:49]
	v_add_u32_e32 v158, 0x22c00, v216
	v_add_u32_e32 v160, 0x23c00, v216
	ds_read_b64_tr_b16 v[158:159], v158
	ds_read_b64_tr_b16 v[160:161], v160
	s_waitcnt lgkmcnt(0)
	v_mfma_f32_32x32x16_bf16 v[18:33], v[130:133], v[154:157], v[18:33]
	v_add_u32_e32 v154, 0x20e00, v216
	v_add_u32_e32 v156, 0x21e00, v216
	ds_read_b64_tr_b16 v[154:155], v154
	ds_read_b64_tr_b16 v[156:157], v156
	v_mfma_f32_32x32x16_bf16 v[2:17], v[138:141], v[150:153], v[2:17]
	v_mfma_f32_32x32x16_bf16 v[18:33], v[134:137], v[158:161], v[18:33]
	v_add_u32_e32 v158, 0x22e00, v216
	v_add_u32_e32 v160, 0x23e00, v216
	ds_read_b64_tr_b16 v[158:159], v158
	ds_read_b64_tr_b16 v[160:161], v160
	s_waitcnt vmcnt(0) lgkmcnt(0)
	s_barrier
	v_mfma_f32_32x32x16_bf16 v[2:17], v[130:133], v[154:157], v[2:17]
	v_mfma_f32_32x32x16_bf16 v[2:17], v[134:137], v[158:161], v[2:17]
	s_and_saveexec_b64 s[2:3], vcc
	v_pk_add_f32 v[130:131], v[194:195], v[196:197]
	s_nop 0
	v_add_f32_e32 v130, v211, v130
	v_add_f32_e32 v130, v130, v131
	v_lshl_add_u32 v131, v205, 2, s93
	ds_write_b32 v131, v130
	s_or_b64 exec, exec, s[2:3]
	v_add_u32_e32 v0, s93, v0
	s_waitcnt lgkmcnt(0)
	ds_read_b128 v[130:133], v0
	ds_read_b128 v[134:137], v0 offset:32
	ds_read_b128 v[138:141], v0 offset:96
	s_waitcnt lgkmcnt(2)
	v_rcp_f32_e32 v144, v130
	v_rcp_f32_e32 v145, v131
	v_rcp_f32_e32 v146, v132
	v_rcp_f32_e32 v147, v133
	ds_read_b128 v[130:133], v0 offset:64
	s_waitcnt lgkmcnt(2)
	v_rcp_f32_e32 v148, v134
	v_rcp_f32_e32 v149, v135
	v_rcp_f32_e32 v150, v136
	v_rcp_f32_e32 v151, v137
	s_waitcnt lgkmcnt(0)
	v_rcp_f32_e32 v152, v130
	v_rcp_f32_e32 v154, v132
	v_rcp_f32_e32 v156, v138
	v_rcp_f32_e32 v158, v140
	v_rcp_f32_e32 v159, v141
	v_rcp_f32_e32 v157, v139
	v_rcp_f32_e32 v155, v133
	v_rcp_f32_e32 v153, v131
	v_pk_mul_f32 v[142:143], v[128:129], v[158:159]
	v_pk_mul_f32 v[140:141], v[126:127], v[156:157]
	v_pk_mul_f32 v[138:139], v[124:125], v[154:155]
	v_pk_mul_f32 v[136:137], v[122:123], v[152:153]
	v_pk_mul_f32 v[134:135], v[120:121], v[150:151]
	v_pk_mul_f32 v[132:133], v[118:119], v[148:149]
	v_pk_mul_f32 v[130:131], v[116:117], v[146:147]
	v_pk_mul_f32 v[128:129], v[114:115], v[144:145]
	v_pk_mul_f32 v[126:127], v[112:113], v[158:159]
	v_pk_mul_f32 v[124:125], v[110:111], v[156:157]
	v_pk_mul_f32 v[122:123], v[108:109], v[154:155]
	v_pk_mul_f32 v[120:121], v[106:107], v[152:153]
	v_pk_mul_f32 v[118:119], v[104:105], v[150:151]
	v_pk_mul_f32 v[116:117], v[102:103], v[148:149]
	v_pk_mul_f32 v[114:115], v[100:101], v[146:147]
	v_pk_mul_f32 v[112:113], v[98:99], v[144:145]
	v_pk_mul_f32 v[110:111], v[96:97], v[158:159]
	v_pk_mul_f32 v[108:109], v[94:95], v[156:157]
	v_pk_mul_f32 v[106:107], v[92:93], v[154:155]
	v_pk_mul_f32 v[104:105], v[90:91], v[152:153]
	v_pk_mul_f32 v[102:103], v[88:89], v[150:151]
	v_pk_mul_f32 v[100:101], v[86:87], v[148:149]
	v_pk_mul_f32 v[98:99], v[84:85], v[146:147]
	v_pk_mul_f32 v[96:97], v[82:83], v[144:145]
	v_pk_mul_f32 v[94:95], v[80:81], v[158:159]
	v_pk_mul_f32 v[92:93], v[78:79], v[156:157]
	v_pk_mul_f32 v[90:91], v[76:77], v[154:155]
	v_pk_mul_f32 v[88:89], v[74:75], v[152:153]
	v_pk_mul_f32 v[86:87], v[72:73], v[150:151]
	v_pk_mul_f32 v[84:85], v[70:71], v[148:149]
	v_pk_mul_f32 v[82:83], v[68:69], v[146:147]
	v_pk_mul_f32 v[80:81], v[66:67], v[144:145]
	v_pk_mul_f32 v[78:79], v[64:65], v[158:159]
	v_pk_mul_f32 v[76:77], v[62:63], v[156:157]
	v_pk_mul_f32 v[74:75], v[60:61], v[154:155]
	v_pk_mul_f32 v[72:73], v[58:59], v[152:153]
	v_pk_mul_f32 v[70:71], v[56:57], v[150:151]
	v_pk_mul_f32 v[68:69], v[54:55], v[148:149]
	v_pk_mul_f32 v[66:67], v[52:53], v[146:147]
	v_pk_mul_f32 v[64:65], v[50:51], v[144:145]
	v_pk_mul_f32 v[62:63], v[48:49], v[158:159]
	v_pk_mul_f32 v[60:61], v[46:47], v[156:157]
	v_pk_mul_f32 v[58:59], v[44:45], v[154:155]
	v_pk_mul_f32 v[56:57], v[42:43], v[152:153]
	v_pk_mul_f32 v[54:55], v[40:41], v[150:151]
	v_pk_mul_f32 v[52:53], v[38:39], v[148:149]
	v_pk_mul_f32 v[50:51], v[36:37], v[146:147]
	v_pk_mul_f32 v[48:49], v[34:35], v[144:145]
	v_pk_mul_f32 v[46:47], v[32:33], v[158:159]
	v_pk_mul_f32 v[44:45], v[30:31], v[156:157]
	v_pk_mul_f32 v[42:43], v[28:29], v[154:155]
	v_pk_mul_f32 v[40:41], v[26:27], v[152:153]
	v_pk_mul_f32 v[38:39], v[24:25], v[150:151]
	v_pk_mul_f32 v[36:37], v[22:23], v[148:149]
	v_pk_mul_f32 v[34:35], v[20:21], v[146:147]
	v_pk_mul_f32 v[32:33], v[18:19], v[144:145]
	v_pk_mul_f32 v[30:31], v[16:17], v[158:159]
	v_pk_mul_f32 v[28:29], v[14:15], v[156:157]
	v_pk_mul_f32 v[26:27], v[12:13], v[154:155]
	v_pk_mul_f32 v[24:25], v[10:11], v[152:153]
	v_pk_mul_f32 v[22:23], v[8:9], v[150:151]
	v_pk_mul_f32 v[20:21], v[6:7], v[148:149]
	v_pk_mul_f32 v[18:19], v[4:5], v[146:147]
	v_pk_mul_f32 v[16:17], v[2:3], v[144:145]
	s_barrier

.LBB0_1254:
	s_and_b64 vcc, exec, s[4:5]
	s_cbranch_vccz .LBB0_1213
	v_mov_b32_e32 v210, v214
	s_mov_b32 m0, s90
	v_and_b32_e32 v205, 31, v210
	v_ashrrev_i32_e32 v16, 5, v210
	v_or_b32_e32 v0, s66, v205
	v_lshlrev_b64 v[2:3], 14, v[0:1]
	v_lshlrev_b32_e32 v4, 3, v16
	v_lshl_add_u64 v[2:3], s[42:43], 0, v[2:3]
	v_ashrrev_i32_e32 v5, 31, v4
	v_lshl_add_u64 v[2:3], v[4:5], 1, v[2:3]
	global_load_dwordx4 v[190:193], v[2:3], off
	global_load_dwordx4 v[186:189], v[2:3], off offset:32
	global_load_dwordx4 v[182:185], v[2:3], off offset:64
	global_load_dwordx4 v[178:181], v[2:3], off offset:96
	global_load_dwordx4 v[174:177], v[2:3], off offset:128
	global_load_dwordx4 v[170:173], v[2:3], off offset:160
	global_load_dwordx4 v[166:169], v[2:3], off offset:192
	global_load_dwordx4 v[162:165], v[2:3], off offset:224
	v_lshlrev_b32_e32 v17, 4, v210
	v_lshlrev_b32_e32 v3, 1, v210
	v_and_b32_e32 v2, 0xc0, v17
	v_and_b32_e32 v3, 32, v3
	v_add_u32_e32 v7, s65, v210
	v_add3_u32 v3, 0, v2, v3
	v_ashrrev_i32_e32 v2, 4, v7
	v_xor_b32_e32 v4, v2, v210
	v_lshlrev_b32_e32 v2, 13, v2
	v_lshlrev_b32_e32 v4, 3, v4
	v_add_u32_e32 v8, 0x200, v7
	v_and_or_b32 v2, v4, s60, v2
	v_ashrrev_i32_e32 v4, 4, v8
	v_xor_b32_e32 v6, v4, v210
	v_lshlrev_b32_e32 v4, 13, v4
	v_lshlrev_b32_e32 v6, 3, v6
	v_and_or_b32 v4, v6, s60, v4
	v_bfe_u32 v6, v210, 2, 2
	v_lshrrev_b32_e32 v9, 1, v210
	v_and_or_b32 v9, v9, 8, v6
	v_ashrrev_i32_e32 v6, 5, v7
	v_and_b32_e32 v10, 0x7fff0, v6
	v_lshrrev_b32_e32 v6, 1, v6
	v_and_b32_e32 v6, 4, v6
	v_ashrrev_i32_e32 v8, 5, v8
	v_or3_b32 v6, v10, v6, v9
	v_and_b32_e32 v10, 0x7fff0, v8
	v_lshrrev_b32_e32 v8, 1, v8
	v_and_b32_e32 v8, 4, v8
	v_or3_b32 v8, v10, v8, v9
	v_add_u32_e32 v10, 0x400, v7
	v_ashrrev_i32_e32 v10, 5, v10
	v_and_b32_e32 v11, 0xe0, v7
	v_and_b32_e32 v12, 0x7fff0, v10
	v_lshrrev_b32_e32 v10, 1, v10
	v_add_u32_e32 v7, 0x600, v7
	v_and_b32_e32 v10, 4, v10
	v_ashrrev_i32_e32 v7, 5, v7
	v_lshlrev_b32_e32 v0, 3, v210
	v_or3_b32 v10, v12, v10, v9
	v_and_b32_e32 v12, 0x7fff0, v7
	v_lshrrev_b32_e32 v7, 1, v7
	v_and_b32_e32 v5, 0x100, v0
	v_and_b32_e32 v0, 24, v0
	v_and_b32_e32 v7, 4, v7
	v_lshlrev_b32_e32 v6, 13, v6
	v_or3_b32 v7, v12, v7, v9
	v_add3_u32 v217, v3, v5, v0
	v_ashrrev_i32_e32 v3, 31, v2
	v_or3_b32 v6, v6, v11, v0
	v_lshlrev_b32_e32 v8, 13, v8
	v_lshlrev_b32_e32 v7, 13, v7
	v_lshlrev_b64 v[2:3], 1, v[2:3]
	v_ashrrev_i32_e32 v5, 31, v4
	v_or3_b32 v8, v8, v11, v0
	v_lshlrev_b32_e32 v10, 13, v10
	v_or3_b32 v12, v7, v11, v0
	v_lshl_add_u64 v[14:15], s[2:3], 0, v[2:3]
	v_lshlrev_b64 v[4:5], 1, v[4:5]
	v_ashrrev_i32_e32 v7, 31, v6
	v_or3_b32 v10, v10, v11, v0
	global_load_lds_dwordx4 v[14:15], off
	v_lshl_add_u64 v[14:15], s[2:3], 0, v[4:5]
	s_add_i32 m0, s90, 0x2000
	v_lshlrev_b64 v[6:7], 1, v[6:7]
	v_ashrrev_i32_e32 v9, 31, v8
	global_load_lds_dwordx4 v[14:15], off
	v_lshl_add_u64 v[14:15], s[40:41], 0, v[6:7]
	s_mov_b32 m0, s94
	v_lshlrev_b64 v[8:9], 1, v[8:9]
	v_ashrrev_i32_e32 v11, 31, v10
	global_load_lds_dwordx4 v[14:15], off
	v_lshl_add_u64 v[14:15], s[40:41], 0, v[8:9]
	s_add_i32 m0, s90, 0xe000
	v_lshlrev_b64 v[10:11], 1, v[10:11]
	global_load_lds_dwordx4 v[14:15], off
	v_lshl_add_u64 v[14:15], s[40:41], 0, v[10:11]
	s_add_i32 m0, s94, 0x4000
	v_ashrrev_i32_e32 v13, 31, v12
	global_load_lds_dwordx4 v[14:15], off
	s_add_i32 m0, s94, 0x6000
	v_lshlrev_b64 v[12:13], 1, v[12:13]
	s_add_u32 s2, s2, 0x100000
	v_lshl_add_u64 v[14:15], s[40:41], 0, v[12:13]
	s_addc_u32 s3, s3, 0
	global_load_lds_dwordx4 v[14:15], off
	v_lshl_add_u64 v[14:15], s[2:3], 0, v[2:3]
	s_add_i32 m0, s90, 0x4000
	v_lshlrev_b32_e32 v0, 4, v16
	global_load_lds_dwordx4 v[14:15], off
	s_add_i32 m0, s90, 0x6000
	v_lshl_add_u64 v[14:15], s[2:3], 0, v[4:5]
	s_add_u32 s2, s40, 0x100000
	s_addc_u32 s3, s41, 0
	global_load_lds_dwordx4 v[14:15], off
	v_lshl_add_u64 v[14:15], s[2:3], 0, v[6:7]
	s_add_i32 m0, s90, 0x14000
	v_mov_b32_e32 v211, 0
	global_load_lds_dwordx4 v[14:15], off
	v_lshl_add_u64 v[14:15], s[2:3], 0, v[8:9]
	s_add_i32 m0, s90, 0x16000
	v_lshl_add_u32 v218, v205, 8, 0
	global_load_lds_dwordx4 v[14:15], off
	v_lshl_add_u64 v[14:15], s[2:3], 0, v[10:11]
	s_add_i32 m0, s90, 0x18000
	v_bitop3_b32 v226, v0, v17, s51 bitop3:0x78
	global_load_lds_dwordx4 v[14:15], off
	v_lshl_add_u64 v[14:15], s[2:3], 0, v[12:13]
	s_add_i32 m0, s90, 0x1a000
	s_add_u32 s4, s38, s36
	global_load_lds_dwordx4 v[14:15], off
	v_add_u32_e32 v14, 32, v0
	v_bitop3_b32 v225, v14, v17, s51 bitop3:0x78
	v_add_u32_e32 v14, 64, v0
	v_bitop3_b32 v224, v14, v17, s51 bitop3:0x78
	v_add_u32_e32 v14, 0x60, v0
	s_addc_u32 s5, s39, s37
	v_bitop3_b32 v223, v14, v17, s51 bitop3:0x78
	v_add_u32_e32 v14, 0x80, v0
	s_add_u32 s2, s57, s4
	v_bitop3_b32 v222, v14, v17, s51 bitop3:0x78
	v_add_u32_e32 v14, 0xa0, v0
	s_addc_u32 s3, s10, s5
	v_bitop3_b32 v221, v14, v17, s51 bitop3:0x78
	v_add_u32_e32 v14, 0xc0, v0
	s_waitcnt vmcnt(0)
	v_lshl_add_u64 v[194:195], s[2:3], 0, v[2:3]
	v_lshl_add_u64 v[196:197], s[2:3], 0, v[4:5]
	s_add_u32 s2, s54, s4
	v_bitop3_b32 v220, v14, v17, s51 bitop3:0x78
	v_add_u32_e32 v14, 0xe0, v0
	s_addc_u32 s3, s55, s5
	v_bitop3_b32 v219, v14, v17, s51 bitop3:0x78
	v_lshl_add_u64 v[198:199], s[2:3], 0, v[6:7]
	v_lshl_add_u64 v[200:201], s[2:3], 0, v[8:9]
	v_lshl_add_u64 v[202:203], s[2:3], 0, v[10:11]
	v_lshl_add_u64 v[208:209], s[2:3], 0, v[12:13]
	s_mov_b32 s4, 0
	s_mov_b64 s[2:3], 0
	v_mov_b32_e32 v2, 0
	v_mov_b32_e32 v3, v211
	v_mov_b32_e32 v4, v211
	v_mov_b32_e32 v5, v211
	v_mov_b32_e32 v6, v211
	v_mov_b32_e32 v7, v211
	v_mov_b32_e32 v8, v211
	v_mov_b32_e32 v9, v211
	v_mov_b32_e32 v10, v211
	v_mov_b32_e32 v11, v211
	v_mov_b32_e32 v12, v211
	v_mov_b32_e32 v13, v211
	v_mov_b32_e32 v14, v211
	v_mov_b32_e32 v15, v211
	v_mov_b32_e32 v16, v211
	v_mov_b32_e32 v17, v211
	v_mov_b32_e32 v18, 0
	v_mov_b32_e32 v19, v211
	v_mov_b32_e32 v20, v211
	v_mov_b32_e32 v21, v211
	v_mov_b32_e32 v22, v211
	v_mov_b32_e32 v23, v211
	v_mov_b32_e32 v24, v211
	v_mov_b32_e32 v25, v211
	v_mov_b32_e32 v26, v211
	v_mov_b32_e32 v27, v211
	v_mov_b32_e32 v28, v211
	v_mov_b32_e32 v29, v211
	v_mov_b32_e32 v30, v211
	v_mov_b32_e32 v31, v211
	v_mov_b32_e32 v32, v211
	v_mov_b32_e32 v33, v211
	v_mov_b32_e32 v34, 0
	v_mov_b32_e32 v35, v211
	v_mov_b32_e32 v36, v211
	v_mov_b32_e32 v37, v211
	v_mov_b32_e32 v38, v211
	v_mov_b32_e32 v39, v211
	v_mov_b32_e32 v40, v211
	v_mov_b32_e32 v41, v211
	v_mov_b32_e32 v42, v211
	v_mov_b32_e32 v43, v211
	v_mov_b32_e32 v44, v211
	v_mov_b32_e32 v45, v211
	v_mov_b32_e32 v46, v211
	v_mov_b32_e32 v47, v211
	v_mov_b32_e32 v48, v211
	v_mov_b32_e32 v49, v211
	v_mov_b32_e32 v50, 0
	v_mov_b32_e32 v51, v211
	v_mov_b32_e32 v52, v211
	v_mov_b32_e32 v53, v211
	v_mov_b32_e32 v54, v211
	v_mov_b32_e32 v55, v211
	v_mov_b32_e32 v56, v211
	v_mov_b32_e32 v57, v211
	v_mov_b32_e32 v58, v211
	v_mov_b32_e32 v59, v211
	v_mov_b32_e32 v60, v211
	v_mov_b32_e32 v61, v211
	v_mov_b32_e32 v62, v211
	v_mov_b32_e32 v63, v211
	v_mov_b32_e32 v64, v211
	v_mov_b32_e32 v65, v211
	v_mov_b32_e32 v66, 0
	v_mov_b32_e32 v67, v211
	v_mov_b32_e32 v68, v211
	v_mov_b32_e32 v69, v211
	v_mov_b32_e32 v70, v211
	v_mov_b32_e32 v71, v211
	v_mov_b32_e32 v72, v211
	v_mov_b32_e32 v73, v211
	v_mov_b32_e32 v74, v211
	v_mov_b32_e32 v75, v211
	v_mov_b32_e32 v76, v211
	v_mov_b32_e32 v77, v211
	v_mov_b32_e32 v78, v211
	v_mov_b32_e32 v79, v211
	v_mov_b32_e32 v80, v211
	v_mov_b32_e32 v81, v211
	v_mov_b32_e32 v82, 0
	v_mov_b32_e32 v83, v211
	v_mov_b32_e32 v84, v211
	v_mov_b32_e32 v85, v211
	v_mov_b32_e32 v86, v211
	v_mov_b32_e32 v87, v211
	v_mov_b32_e32 v88, v211
	v_mov_b32_e32 v89, v211
	v_mov_b32_e32 v90, v211
	v_mov_b32_e32 v91, v211
	v_mov_b32_e32 v92, v211
	v_mov_b32_e32 v93, v211
	v_mov_b32_e32 v94, v211
	v_mov_b32_e32 v95, v211
	v_mov_b32_e32 v96, v211
	v_mov_b32_e32 v97, v211
	v_mov_b32_e32 v98, 0
	v_mov_b32_e32 v99, v211
	v_mov_b32_e32 v100, v211
	v_mov_b32_e32 v101, v211
	v_mov_b32_e32 v102, v211
	v_mov_b32_e32 v103, v211
	v_mov_b32_e32 v104, v211
	v_mov_b32_e32 v105, v211
	v_mov_b32_e32 v106, v211
	v_mov_b32_e32 v107, v211
	v_mov_b32_e32 v108, v211
	v_mov_b32_e32 v109, v211
	v_mov_b32_e32 v110, v211
	v_mov_b32_e32 v111, v211
	v_mov_b32_e32 v112, v211
	v_mov_b32_e32 v113, v211
	v_mov_b32_e32 v114, 0
	v_mov_b32_e32 v115, v211
	v_mov_b32_e32 v116, v211
	v_mov_b32_e32 v117, v211
	v_mov_b32_e32 v118, v211
	v_mov_b32_e32 v119, v211
	v_mov_b32_e32 v120, v211
	v_mov_b32_e32 v121, v211
	v_mov_b32_e32 v122, v211
	v_mov_b32_e32 v123, v211
	v_mov_b32_e32 v124, v211
	v_mov_b32_e32 v125, v211
	v_mov_b32_e32 v126, v211
	v_mov_b32_e32 v127, v211
	v_mov_b32_e32 v128, v211
	v_mov_b32_e32 v129, v211
	s_cmp_lt_u32 s66, 0x80
	s_cbranch_scc1 .Lst2_a
	s_barrier
.Lst2_a:
.LBB0_1256:
	s_waitcnt vmcnt(6)
	s_waitcnt lgkmcnt(0)
	s_barrier
	v_lshl_add_u32 v227, s4, 14, v218
	v_add_u32_e32 v134, v227, v226
	v_add_u32_e32 v232, v227, v225
	ds_read_b128 v[130:133], v134
	ds_read_b128 v[134:137], v134 offset:8192
	s_waitcnt lgkmcnt(0)
	v_mfma_f32_32x32x16_bf16 v[146:161], v[130:133], v[190:193], 0
	ds_read_b128 v[228:231], v232
	ds_read_b128 v[232:235], v232 offset:8192
	s_add_i32 s5, s4, 1
	s_cmp_lg_u32 s4, 2
	v_mfma_f32_32x32x16_bf16 v[130:145], v[134:137], v[190:193], 0
	s_waitcnt lgkmcnt(0)
	v_mfma_f32_32x32x16_bf16 v[130:145], v[232:235], v[186:189], v[130:145]
	v_add_u32_e32 v232, v227, v224
	v_mfma_f32_32x32x16_bf16 v[146:161], v[228:231], v[186:189], v[146:161]
	ds_read_b128 v[228:231], v232
	ds_read_b128 v[232:235], v232 offset:8192
	s_waitcnt lgkmcnt(0)
	v_mfma_f32_32x32x16_bf16 v[130:145], v[232:235], v[182:185], v[130:145]
	v_add_u32_e32 v232, v227, v223
	v_mfma_f32_32x32x16_bf16 v[146:161], v[228:231], v[182:185], v[146:161]
	ds_read_b128 v[228:231], v232
	ds_read_b128 v[232:235], v232 offset:8192
	s_waitcnt lgkmcnt(0)
	v_mfma_f32_32x32x16_bf16 v[130:145], v[232:235], v[178:181], v[130:145]
	v_add_u32_e32 v232, v227, v222
	v_mfma_f32_32x32x16_bf16 v[146:161], v[228:231], v[178:181], v[146:161]
	ds_read_b128 v[228:231], v232
	ds_read_b128 v[232:235], v232 offset:8192
	s_waitcnt lgkmcnt(0)
	v_mfma_f32_32x32x16_bf16 v[130:145], v[232:235], v[174:177], v[130:145]
	v_add_u32_e32 v232, v227, v221
	v_mfma_f32_32x32x16_bf16 v[146:161], v[228:231], v[174:177], v[146:161]
	ds_read_b128 v[228:231], v232
	ds_read_b128 v[232:235], v232 offset:8192
	s_waitcnt lgkmcnt(0)
	v_mfma_f32_32x32x16_bf16 v[130:145], v[232:235], v[170:173], v[130:145]
	v_add_u32_e32 v232, v227, v220
	v_add_u32_e32 v227, v227, v219
	v_mfma_f32_32x32x16_bf16 v[146:161], v[228:231], v[170:173], v[146:161]
	ds_read_b128 v[228:231], v232
	ds_read_b128 v[232:235], v232 offset:8192
	s_waitcnt lgkmcnt(0)
	v_mfma_f32_32x32x16_bf16 v[130:145], v[232:235], v[166:169], v[130:145]
	v_mfma_f32_32x32x16_bf16 v[146:161], v[228:231], v[166:169], v[146:161]
	ds_read_b128 v[228:231], v227
	ds_read_b128 v[232:235], v227 offset:8192
	s_waitcnt lgkmcnt(0)
	v_mfma_f32_32x32x16_bf16 v[130:145], v[232:235], v[162:165], v[130:145]
	v_mfma_f32_32x32x16_bf16 v[146:161], v[228:231], v[162:165], v[146:161]
	s_nop 10
	v_fmamk_f32 v138, v138, 0x3e0293ee, v215
	v_fmamk_f32 v139, v139, 0x3e0293ee, v215
	v_fmamk_f32 v140, v140, 0x3e0293ee, v215
	v_fmamk_f32 v141, v141, 0x3e0293ee, v215
	v_fmamk_f32 v142, v142, 0x3e0293ee, v215
	v_exp_f32_e32 v227, v138
	v_fmamk_f32 v130, v130, 0x3e0293ee, v215
	v_fmamk_f32 v138, v155, 0x3e0293ee, v215
	v_exp_f32_e32 v155, v139
	v_fmamk_f32 v139, v156, 0x3e0293ee, v215
	v_exp_f32_e32 v156, v140
	v_fmamk_f32 v140, v157, 0x3e0293ee, v215
	v_exp_f32_e32 v157, v141
	v_fmamk_f32 v141, v158, 0x3e0293ee, v215
	v_exp_f32_e32 v158, v142
	v_fmamk_f32 v142, v159, 0x3e0293ee, v215
	v_fmamk_f32 v146, v146, 0x3e0293ee, v215
	v_exp_f32_e32 v159, v142
	v_fmamk_f32 v142, v143, 0x3e0293ee, v215
	v_exp_f32_e32 v146, v146
	v_fmamk_f32 v147, v147, 0x3e0293ee, v215
	v_exp_f32_e32 v228, v142
	v_fmamk_f32 v142, v160, 0x3e0293ee, v215
	v_exp_f32_e32 v147, v147
	v_fmamk_f32 v148, v148, 0x3e0293ee, v215
	v_exp_f32_e32 v160, v142
	v_fmamk_f32 v142, v144, 0x3e0293ee, v215
	v_exp_f32_e32 v148, v148
	v_fmamk_f32 v149, v149, 0x3e0293ee, v215
	v_exp_f32_e32 v229, v142
	v_fmamk_f32 v142, v161, 0x3e0293ee, v215
	v_exp_f32_e32 v149, v149
	v_fmamk_f32 v150, v150, 0x3e0293ee, v215
	v_exp_f32_e32 v161, v142
	v_fmamk_f32 v142, v145, 0x3e0293ee, v215
	v_exp_f32_e32 v150, v150
	v_fmamk_f32 v151, v151, 0x3e0293ee, v215
	v_exp_f32_e32 v230, v142
	v_add_f32_e32 v142, 0, v146
	v_exp_f32_e32 v151, v151
	v_fmamk_f32 v152, v152, 0x3e0293ee, v215
	v_add_f32_e32 v142, v147, v142
	v_exp_f32_e32 v152, v152
	v_fmamk_f32 v153, v153, 0x3e0293ee, v215
	v_add_f32_e32 v142, v148, v142
	v_exp_f32_e32 v153, v153
	v_fmamk_f32 v154, v154, 0x3e0293ee, v215
	v_add_f32_e32 v142, v149, v142
	v_exp_f32_e32 v154, v154
	v_add_f32_e32 v142, v150, v142
	v_exp_f32_e32 v138, v138
	v_add_f32_e32 v142, v151, v142
	v_exp_f32_e32 v139, v139
	v_add_f32_e32 v142, v152, v142
	v_exp_f32_e32 v140, v140
	v_add_f32_e32 v142, v153, v142
	v_exp_f32_e32 v141, v141
	v_add_f32_e32 v142, v154, v142
	v_add_f32_e32 v142, v138, v142
	v_add_f32_e32 v142, v139, v142
	v_add_f32_e32 v142, v140, v142
	v_exp_f32_e32 v130, v130
	v_fmamk_f32 v131, v131, 0x3e0293ee, v215
	v_add_f32_e32 v142, v141, v142
	v_exp_f32_e32 v131, v131
	v_fmamk_f32 v132, v132, 0x3e0293ee, v215
	v_add_f32_e32 v142, v159, v142
	v_exp_f32_e32 v132, v132
	v_fmamk_f32 v133, v133, 0x3e0293ee, v215
	v_add_f32_e32 v142, v160, v142
	v_exp_f32_e32 v133, v133
	v_fmamk_f32 v134, v134, 0x3e0293ee, v215
	v_add_f32_e32 v142, v161, v142
	v_exp_f32_e32 v134, v134
	v_fmamk_f32 v135, v135, 0x3e0293ee, v215
	v_add_f32_e32 v142, v130, v142
	v_exp_f32_e32 v135, v135
	v_fmamk_f32 v136, v136, 0x3e0293ee, v215
	v_add_f32_e32 v142, v131, v142
	v_exp_f32_e32 v136, v136
	v_fmamk_f32 v137, v137, 0x3e0293ee, v215
	v_add_f32_e32 v142, v132, v142
	v_exp_f32_e32 v137, v137
	v_add_f32_e32 v142, v133, v142
	v_add_f32_e32 v142, v134, v142
	v_add_f32_e32 v142, v135, v142
	v_add_f32_e32 v142, v136, v142
	v_add_f32_e32 v142, v137, v142
	v_add_f32_e32 v142, v227, v142
	v_add_f32_e32 v142, v155, v142
	v_add_f32_e32 v142, v156, v142
	v_add_f32_e32 v142, v157, v142
	v_add_f32_e32 v142, v158, v142
	v_add_f32_e32 v142, v228, v142
	v_add_f32_e32 v142, v229, v142
	v_add_f32_e32 v142, v230, v142
	v_mov_b32_e32 v143, v142
	s_nop 1
	v_permlane32_swap_b32_e32 v142, v143
	v_add_f32_e32 v142, v142, v143
	v_add_f32_e32 v211, v211, v142
	v_cvt_pk_bf16_f32 v142, v146, v147
	v_cvt_pk_bf16_f32 v143, v148, v149
	v_cvt_pk_bf16_f32 v144, v150, v151
	v_cvt_pk_bf16_f32 v145, v152, v153
	s_nop 0
	v_permlane32_swap_b32_e32 v142, v144
	v_permlane32_swap_b32_e32 v143, v145
	v_lshl_add_u32 v146, s4, 15, v217
	v_cvt_pk_bf16_f32 v138, v154, v138
	v_cvt_pk_bf16_f32 v139, v139, v140
	v_cvt_pk_bf16_f32 v140, v141, v159
	v_cvt_pk_bf16_f32 v141, v160, v161
	v_cvt_pk_bf16_f32 v130, v130, v131
	v_cvt_pk_bf16_f32 v131, v132, v133
	v_cvt_pk_bf16_f32 v132, v134, v135
	v_cvt_pk_bf16_f32 v133, v136, v137
	v_cvt_pk_bf16_f32 v134, v227, v155
	v_cvt_pk_bf16_f32 v135, v156, v157
	v_cvt_pk_bf16_f32 v136, v158, v228
	v_cvt_pk_bf16_f32 v137, v229, v230
	v_add_u32_e32 v152, 0xc000, v146
	s_waitcnt vmcnt(0)
	s_barrier
	s_add_i32 s98, s4, -1
	s_cmp_eq_u32 s4, 0
	s_cselect_b32 s98, 2, s98
	s_lshl_b32 s99, s98, 14
	s_add_i32 s99, s90, s99
	s_lshl_b32 s98, s98, 15
	s_add_i32 s98, s90, s98
	v_lshl_add_u64 v[236:237], v[194:195], 0, s[2:3]
	s_mov_b32 m0, s99
	s_nop 0
	global_load_lds_dwordx4 v[236:237], off
	v_lshl_add_u64 v[236:237], v[196:197], 0, s[2:3]
	s_add_i32 m0, s99, 0x2000
	s_nop 0
	global_load_lds_dwordx4 v[236:237], off
	v_lshl_add_u64 v[236:237], v[198:199], 0, s[2:3]
	s_add_i32 m0, s98, 0xc000
	s_nop 0
	global_load_lds_dwordx4 v[236:237], off
	v_lshl_add_u64 v[236:237], v[200:201], 0, s[2:3]
	s_add_i32 m0, s98, 0xe000
	s_nop 0
	global_load_lds_dwordx4 v[236:237], off
	v_lshl_add_u64 v[236:237], v[202:203], 0, s[2:3]
	s_add_i32 m0, s98, 0x10000
	s_nop 0
	global_load_lds_dwordx4 v[236:237], off
	v_lshl_add_u64 v[236:237], v[208:209], 0, s[2:3]
	s_add_i32 m0, s98, 0x12000
	s_nop 0
	global_load_lds_dwordx4 v[236:237], off
	s_cmp_lg_u32 s4, 2
	ds_read_b64_tr_b16 v[148:149], v146 offset:49152
	ds_read_b64_tr_b16 v[150:151], v146 offset:53248
	ds_read_b64_tr_b16 v[154:155], v146 offset:57344
	ds_read_b64_tr_b16 v[156:157], v146 offset:61440
	ds_read_b64_tr_b16 v[158:159], v152 offset:16384
	ds_read_b64_tr_b16 v[160:161], v152 offset:20480
	ds_read_b64_tr_b16 v[228:229], v152 offset:24576
	ds_read_b64_tr_b16 v[230:231], v152 offset:28672
	s_waitcnt lgkmcnt(0)
	v_mfma_f32_32x32x16_bf16 v[114:129], v[142:145], v[148:151], v[114:129]
	v_permlane32_swap_b32_e32 v138, v140
	v_permlane32_swap_b32_e32 v139, v141
	v_permlane32_swap_b32_e32 v130, v132
	v_permlane32_swap_b32_e32 v131, v133
	v_mfma_f32_32x32x16_bf16 v[114:129], v[138:141], v[154:157], v[114:129]
	v_permlane32_swap_b32_e32 v134, v136
	v_permlane32_swap_b32_e32 v135, v137
	s_cselect_b32 s4, s5, 0
	s_add_u32 s2, s2, 0x100000
	s_addc_u32 s3, s3, 0
	v_mfma_f32_32x32x16_bf16 v[114:129], v[130:133], v[158:161], v[114:129]
	s_cmp_eq_u32 s2, 0x2200000
	v_mfma_f32_32x32x16_bf16 v[114:129], v[134:137], v[228:231], v[114:129]
	ds_read_b64_tr_b16 v[148:149], v146 offset:49664
	ds_read_b64_tr_b16 v[150:151], v146 offset:53760
	ds_read_b64_tr_b16 v[154:155], v146 offset:57856
	ds_read_b64_tr_b16 v[156:157], v146 offset:61952
	ds_read_b64_tr_b16 v[158:159], v152 offset:16896
	ds_read_b64_tr_b16 v[160:161], v152 offset:20992
	ds_read_b64_tr_b16 v[228:229], v152 offset:25088
	ds_read_b64_tr_b16 v[230:231], v152 offset:29184
	s_waitcnt lgkmcnt(0)
	v_mfma_f32_32x32x16_bf16 v[98:113], v[142:145], v[148:151], v[98:113]
	v_mfma_f32_32x32x16_bf16 v[98:113], v[138:141], v[154:157], v[98:113]
	v_mfma_f32_32x32x16_bf16 v[98:113], v[130:133], v[158:161], v[98:113]
	v_mfma_f32_32x32x16_bf16 v[98:113], v[134:137], v[228:231], v[98:113]
	ds_read_b64_tr_b16 v[148:149], v146 offset:50176
	ds_read_b64_tr_b16 v[150:151], v146 offset:54272
	ds_read_b64_tr_b16 v[154:155], v146 offset:58368
	ds_read_b64_tr_b16 v[156:157], v146 offset:62464
	ds_read_b64_tr_b16 v[158:159], v152 offset:17408
	ds_read_b64_tr_b16 v[160:161], v152 offset:21504
	ds_read_b64_tr_b16 v[228:229], v152 offset:25600
	ds_read_b64_tr_b16 v[230:231], v152 offset:29696
	s_waitcnt lgkmcnt(0)
	v_mfma_f32_32x32x16_bf16 v[82:97], v[142:145], v[148:151], v[82:97]
	v_mfma_f32_32x32x16_bf16 v[82:97], v[138:141], v[154:157], v[82:97]
	v_mfma_f32_32x32x16_bf16 v[82:97], v[130:133], v[158:161], v[82:97]
	v_mfma_f32_32x32x16_bf16 v[82:97], v[134:137], v[228:231], v[82:97]
	ds_read_b64_tr_b16 v[148:149], v146 offset:50688
	ds_read_b64_tr_b16 v[150:151], v146 offset:54784
	ds_read_b64_tr_b16 v[154:155], v146 offset:58880
	ds_read_b64_tr_b16 v[156:157], v146 offset:62976
	ds_read_b64_tr_b16 v[158:159], v152 offset:17920
	ds_read_b64_tr_b16 v[160:161], v152 offset:22016
	ds_read_b64_tr_b16 v[228:229], v152 offset:26112
	ds_read_b64_tr_b16 v[230:231], v152 offset:30208
	s_waitcnt lgkmcnt(0)
	v_mfma_f32_32x32x16_bf16 v[66:81], v[142:145], v[148:151], v[66:81]
	v_mfma_f32_32x32x16_bf16 v[66:81], v[138:141], v[154:157], v[66:81]
	v_mfma_f32_32x32x16_bf16 v[66:81], v[130:133], v[158:161], v[66:81]
	v_mfma_f32_32x32x16_bf16 v[66:81], v[134:137], v[228:231], v[66:81]
	ds_read_b64_tr_b16 v[148:149], v146 offset:51200
	ds_read_b64_tr_b16 v[150:151], v146 offset:55296
	ds_read_b64_tr_b16 v[154:155], v146 offset:59392
	ds_read_b64_tr_b16 v[156:157], v146 offset:63488
	ds_read_b64_tr_b16 v[158:159], v152 offset:18432
	ds_read_b64_tr_b16 v[160:161], v152 offset:22528
	ds_read_b64_tr_b16 v[228:229], v152 offset:26624
	ds_read_b64_tr_b16 v[230:231], v152 offset:30720
	s_waitcnt lgkmcnt(0)
	v_mfma_f32_32x32x16_bf16 v[50:65], v[142:145], v[148:151], v[50:65]
	v_mfma_f32_32x32x16_bf16 v[50:65], v[138:141], v[154:157], v[50:65]
	v_mfma_f32_32x32x16_bf16 v[50:65], v[130:133], v[158:161], v[50:65]
	v_mfma_f32_32x32x16_bf16 v[50:65], v[134:137], v[228:231], v[50:65]
	ds_read_b64_tr_b16 v[148:149], v146 offset:51712
	ds_read_b64_tr_b16 v[150:151], v146 offset:55808
	ds_read_b64_tr_b16 v[154:155], v146 offset:59904
	ds_read_b64_tr_b16 v[156:157], v146 offset:64000
	ds_read_b64_tr_b16 v[158:159], v152 offset:18944
	ds_read_b64_tr_b16 v[160:161], v152 offset:23040
	ds_read_b64_tr_b16 v[228:229], v152 offset:27136
	ds_read_b64_tr_b16 v[230:231], v152 offset:31232
	s_waitcnt lgkmcnt(0)
	v_mfma_f32_32x32x16_bf16 v[34:49], v[142:145], v[148:151], v[34:49]
	v_mfma_f32_32x32x16_bf16 v[34:49], v[138:141], v[154:157], v[34:49]
	v_mfma_f32_32x32x16_bf16 v[34:49], v[130:133], v[158:161], v[34:49]
	v_mfma_f32_32x32x16_bf16 v[34:49], v[134:137], v[228:231], v[34:49]
	ds_read_b64_tr_b16 v[148:149], v146 offset:52224
	ds_read_b64_tr_b16 v[150:151], v146 offset:56320
	ds_read_b64_tr_b16 v[154:155], v146 offset:60416
	ds_read_b64_tr_b16 v[156:157], v146 offset:64512
	ds_read_b64_tr_b16 v[158:159], v152 offset:19456
	ds_read_b64_tr_b16 v[160:161], v152 offset:23552
	ds_read_b64_tr_b16 v[228:229], v152 offset:27648
	ds_read_b64_tr_b16 v[230:231], v152 offset:31744
	s_waitcnt lgkmcnt(0)
	v_mfma_f32_32x32x16_bf16 v[18:33], v[142:145], v[148:151], v[18:33]
	v_mfma_f32_32x32x16_bf16 v[18:33], v[138:141], v[154:157], v[18:33]
	v_mfma_f32_32x32x16_bf16 v[18:33], v[130:133], v[158:161], v[18:33]
	ds_read_b64_tr_b16 v[158:159], v146 offset:52736
	ds_read_b64_tr_b16 v[160:161], v146 offset:56832
	ds_read_b64_tr_b16 v[154:155], v146 offset:60928
	ds_read_b64_tr_b16 v[156:157], v146 offset:65024
	ds_read_b64_tr_b16 v[146:147], v152 offset:19968
	ds_read_b64_tr_b16 v[148:149], v152 offset:24064
	ds_read_b64_tr_b16 v[150:151], v152 offset:28160
	ds_read_b64_tr_b16 v[152:153], v152 offset:32256
	s_waitcnt lgkmcnt(0)
	v_mfma_f32_32x32x16_bf16 v[2:17], v[142:145], v[158:161], v[2:17]
	v_mfma_f32_32x32x16_bf16 v[2:17], v[138:141], v[154:157], v[2:17]
	v_mfma_f32_32x32x16_bf16 v[2:17], v[130:133], v[146:149], v[2:17]
	v_mfma_f32_32x32x16_bf16 v[18:33], v[134:137], v[228:231], v[18:33]
	v_mfma_f32_32x32x16_bf16 v[2:17], v[134:137], v[150:153], v[2:17]
	s_cbranch_scc0 .LBB0_1256
	s_cmp_ge_u32 s66, 0x80
	s_cbranch_scc1 .Lst2_b
	s_barrier
.Lst2_b:
	s_waitcnt vmcnt(6)
	v_lshl_add_u32 v202, s4, 14, v218
	s_waitcnt lgkmcnt(0)
	s_barrier
	v_add_u32_e32 v134, v202, v226
	ds_read_b128 v[130:133], v134
	ds_read_b128 v[146:149], v134 offset:8192
	s_waitcnt lgkmcnt(0)
	v_mfma_f32_32x32x16_bf16 v[130:145], v[130:133], v[190:193], 0
	v_add_u32_e32 v198, v202, v225
	ds_read_b128 v[194:197], v198
	ds_read_b128 v[198:201], v198 offset:8192
	v_cmp_gt_u32_e32 vcc, 32, v210
	v_mfma_f32_32x32x16_bf16 v[146:161], v[146:149], v[190:193], 0
	s_waitcnt lgkmcnt(0)
	v_mfma_f32_32x32x16_bf16 v[130:145], v[194:197], v[186:189], v[130:145]
	v_mfma_f32_32x32x16_bf16 v[146:161], v[198:201], v[186:189], v[146:161]
	v_add_u32_e32 v198, v202, v224
	ds_read_b128 v[194:197], v198
	ds_read_b128 v[198:201], v198 offset:8192
	s_waitcnt lgkmcnt(0)
	v_mfma_f32_32x32x16_bf16 v[130:145], v[194:197], v[182:185], v[130:145]
	v_mfma_f32_32x32x16_bf16 v[146:161], v[198:201], v[182:185], v[146:161]
	v_add_u32_e32 v198, v202, v223
	ds_read_b128 v[194:197], v198
	ds_read_b128 v[198:201], v198 offset:8192
	s_waitcnt lgkmcnt(0)
	v_mfma_f32_32x32x16_bf16 v[130:145], v[194:197], v[178:181], v[130:145]
	v_mfma_f32_32x32x16_bf16 v[146:161], v[198:201], v[178:181], v[146:161]
	v_add_u32_e32 v198, v202, v222
	ds_read_b128 v[194:197], v198
	ds_read_b128 v[198:201], v198 offset:8192
	s_waitcnt lgkmcnt(0)
	v_mfma_f32_32x32x16_bf16 v[130:145], v[194:197], v[174:177], v[130:145]
	v_mfma_f32_32x32x16_bf16 v[146:161], v[198:201], v[174:177], v[146:161]
	v_add_u32_e32 v198, v202, v221
	ds_read_b128 v[194:197], v198
	ds_read_b128 v[198:201], v198 offset:8192
	s_waitcnt lgkmcnt(0)
	v_mfma_f32_32x32x16_bf16 v[130:145], v[194:197], v[170:173], v[130:145]
	v_mfma_f32_32x32x16_bf16 v[146:161], v[198:201], v[170:173], v[146:161]
	v_add_u32_e32 v198, v202, v220
	ds_read_b128 v[194:197], v198
	ds_read_b128 v[198:201], v198 offset:8192
	s_waitcnt lgkmcnt(0)
	v_mfma_f32_32x32x16_bf16 v[130:145], v[194:197], v[166:169], v[130:145]
	v_mfma_f32_32x32x16_bf16 v[146:161], v[198:201], v[166:169], v[146:161]
	v_add_u32_e32 v198, v202, v219
	ds_read_b128 v[194:197], v198
	ds_read_b128 v[198:201], v198 offset:8192
	s_waitcnt lgkmcnt(0)
	v_mfma_f32_32x32x16_bf16 v[130:145], v[194:197], v[162:165], v[130:145]
	v_add_u32_e32 v195, v218, v225
	v_mfma_f32_32x32x16_bf16 v[146:161], v[198:201], v[162:165], v[146:161]
	s_nop 9
	v_fmamk_f32 v130, v130, 0x3e0293ee, v215
	v_exp_f32_e32 v130, v130
	v_fmamk_f32 v131, v131, 0x3e0293ee, v215
	v_exp_f32_e32 v131, v131
	v_fmamk_f32 v132, v132, 0x3e0293ee, v215
	v_exp_f32_e32 v132, v132
	v_fmamk_f32 v133, v133, 0x3e0293ee, v215
	v_exp_f32_e32 v133, v133
	v_fmamk_f32 v134, v134, 0x3e0293ee, v215
	v_exp_f32_e32 v134, v134
	v_fmamk_f32 v135, v135, 0x3e0293ee, v215
	v_add_f32_e32 v194, 0, v130
	v_exp_f32_e32 v135, v135
	v_fmamk_f32 v136, v136, 0x3e0293ee, v215
	v_add_f32_e32 v194, v131, v194
	v_exp_f32_e32 v136, v136
	v_fmamk_f32 v137, v137, 0x3e0293ee, v215
	v_add_f32_e32 v194, v132, v194
	v_exp_f32_e32 v137, v137
	v_fmamk_f32 v138, v138, 0x3e0293ee, v215
	v_add_f32_e32 v194, v133, v194
	v_exp_f32_e32 v138, v138
	v_fmamk_f32 v139, v139, 0x3e0293ee, v215
	v_add_f32_e32 v194, v134, v194
	v_exp_f32_e32 v139, v139
	v_fmamk_f32 v140, v140, 0x3e0293ee, v215
	v_add_f32_e32 v194, v135, v194
	v_exp_f32_e32 v140, v140
	v_fmamk_f32 v141, v141, 0x3e0293ee, v215
	v_add_f32_e32 v194, v136, v194
	v_exp_f32_e32 v141, v141
	v_fmamk_f32 v142, v142, 0x3e0293ee, v215
	v_add_f32_e32 v194, v137, v194
	v_exp_f32_e32 v142, v142
	v_fmamk_f32 v143, v143, 0x3e0293ee, v215
	v_add_f32_e32 v194, v138, v194
	v_exp_f32_e32 v143, v143
	v_fmamk_f32 v144, v144, 0x3e0293ee, v215
	v_add_f32_e32 v194, v139, v194
	v_exp_f32_e32 v144, v144
	v_fmamk_f32 v145, v145, 0x3e0293ee, v215
	v_add_f32_e32 v194, v140, v194
	v_fmamk_f32 v146, v146, 0x3e0293ee, v215
	v_exp_f32_e32 v145, v145
	v_add_f32_e32 v194, v141, v194
	v_exp_f32_e32 v146, v146
	v_fmamk_f32 v147, v147, 0x3e0293ee, v215
	v_add_f32_e32 v194, v142, v194
	v_exp_f32_e32 v147, v147
	v_fmamk_f32 v148, v148, 0x3e0293ee, v215
	v_add_f32_e32 v194, v143, v194
	v_exp_f32_e32 v148, v148
	v_fmamk_f32 v149, v149, 0x3e0293ee, v215
	v_add_f32_e32 v194, v144, v194
	v_exp_f32_e32 v149, v149
	v_fmamk_f32 v150, v150, 0x3e0293ee, v215
	v_add_f32_e32 v194, v145, v194
	v_exp_f32_e32 v150, v150
	v_fmamk_f32 v151, v151, 0x3e0293ee, v215
	v_add_f32_e32 v194, v146, v194
	v_exp_f32_e32 v151, v151
	v_fmamk_f32 v152, v152, 0x3e0293ee, v215
	v_add_f32_e32 v194, v147, v194
	v_exp_f32_e32 v152, v152
	v_fmamk_f32 v153, v153, 0x3e0293ee, v215
	v_add_f32_e32 v194, v148, v194
	v_exp_f32_e32 v153, v153
	v_fmamk_f32 v154, v154, 0x3e0293ee, v215
	v_add_f32_e32 v194, v149, v194
	v_exp_f32_e32 v154, v154
	v_fmamk_f32 v155, v155, 0x3e0293ee, v215
	v_add_f32_e32 v194, v150, v194
	v_exp_f32_e32 v155, v155
	v_fmamk_f32 v156, v156, 0x3e0293ee, v215
	v_add_f32_e32 v194, v151, v194
	v_exp_f32_e32 v156, v156
	v_fmamk_f32 v157, v157, 0x3e0293ee, v215
	v_add_f32_e32 v194, v152, v194
	v_exp_f32_e32 v157, v157
	v_fmamk_f32 v158, v158, 0x3e0293ee, v215
	v_add_f32_e32 v194, v153, v194
	v_cvt_pk_bf16_f32 v130, v130, v131
	v_cvt_pk_bf16_f32 v131, v132, v133
	v_cvt_pk_bf16_f32 v132, v134, v135
	v_cvt_pk_bf16_f32 v133, v136, v137
	v_exp_f32_e32 v158, v158
	v_fmamk_f32 v159, v159, 0x3e0293ee, v215
	v_add_f32_e32 v194, v154, v194
	v_permlane32_swap_b32_e32 v130, v132
	v_permlane32_swap_b32_e32 v131, v133
	v_exp_f32_e32 v159, v159
	v_add_f32_e32 v194, v155, v194
	v_add_f32_e32 v194, v156, v194
	v_add_f32_e32 v194, v157, v194
	v_add_f32_e32 v194, v158, v194
	v_cvt_pk_bf16_f32 v134, v138, v139
	v_cvt_pk_bf16_f32 v138, v146, v147
	v_lshl_add_u32 v147, s4, 15, v217
	v_add_f32_e32 v194, v159, v194
	v_cvt_pk_bf16_f32 v135, v140, v141
	v_cvt_pk_bf16_f32 v136, v142, v143
	v_cvt_pk_bf16_f32 v137, v144, v145
	v_cvt_pk_bf16_f32 v139, v148, v149
	v_cvt_pk_bf16_f32 v140, v150, v151
	v_cvt_pk_bf16_f32 v141, v152, v153
	v_cvt_pk_bf16_f32 v142, v154, v155
	v_cvt_pk_bf16_f32 v143, v156, v157
	v_cvt_pk_bf16_f32 v144, v158, v159
	v_add_u32_e32 v146, 0xc000, v147
	ds_read_b64_tr_b16 v[148:149], v147 offset:49152
	ds_read_b64_tr_b16 v[150:151], v147 offset:53248
	ds_read_b64_tr_b16 v[152:153], v147 offset:57344
	ds_read_b64_tr_b16 v[154:155], v147 offset:61440
	ds_read_b64_tr_b16 v[156:157], v146 offset:16384
	ds_read_b64_tr_b16 v[158:159], v146 offset:20480
	ds_read_b64_tr_b16 v[198:199], v146 offset:24576
	ds_read_b64_tr_b16 v[200:201], v146 offset:28672
	s_waitcnt lgkmcnt(0)
	v_mfma_f32_32x32x16_bf16 v[114:129], v[130:133], v[148:151], v[114:129]
	v_permlane32_swap_b32_e32 v134, v136
	v_permlane32_swap_b32_e32 v135, v137
	v_permlane32_swap_b32_e32 v138, v140
	v_permlane32_swap_b32_e32 v139, v141
	v_mfma_f32_32x32x16_bf16 v[114:129], v[134:137], v[152:155], v[114:129]
	v_fmamk_f32 v160, v160, 0x3e0293ee, v215
	v_fmamk_f32 v161, v161, 0x3e0293ee, v215
	v_exp_f32_e32 v160, v160
	v_exp_f32_e32 v161, v161
	v_permlane32_swap_b32_e32 v142, v144
	v_add_f32_e32 v194, v160, v194
	v_mfma_f32_32x32x16_bf16 v[114:129], v[138:141], v[156:159], v[114:129]
	v_cvt_pk_bf16_f32 v145, v160, v161
	s_nop 1
	v_permlane32_swap_b32_e32 v143, v145
	v_add_f32_e32 v194, v161, v194
	v_mov_b32_e32 v196, v194
	s_nop 1
	v_permlane32_swap_b32_e32 v194, v196
	v_mfma_f32_32x32x16_bf16 v[114:129], v[142:145], v[198:201], v[114:129]
	ds_read_b64_tr_b16 v[148:149], v147 offset:49664
	ds_read_b64_tr_b16 v[150:151], v147 offset:53760
	ds_read_b64_tr_b16 v[152:153], v147 offset:57856
	ds_read_b64_tr_b16 v[154:155], v147 offset:61952
	ds_read_b64_tr_b16 v[156:157], v146 offset:16896
	ds_read_b64_tr_b16 v[158:159], v146 offset:20992
	ds_read_b64_tr_b16 v[198:199], v146 offset:25088
	ds_read_b64_tr_b16 v[200:201], v146 offset:29184
	s_waitcnt lgkmcnt(0)
	v_mfma_f32_32x32x16_bf16 v[98:113], v[130:133], v[148:151], v[98:113]
	v_mfma_f32_32x32x16_bf16 v[98:113], v[134:137], v[152:155], v[98:113]
	v_mfma_f32_32x32x16_bf16 v[98:113], v[138:141], v[156:159], v[98:113]
	v_mfma_f32_32x32x16_bf16 v[98:113], v[142:145], v[198:201], v[98:113]
	ds_read_b64_tr_b16 v[148:149], v147 offset:50176
	ds_read_b64_tr_b16 v[150:151], v147 offset:54272
	ds_read_b64_tr_b16 v[152:153], v147 offset:58368
	ds_read_b64_tr_b16 v[154:155], v147 offset:62464
	ds_read_b64_tr_b16 v[156:157], v146 offset:17408
	ds_read_b64_tr_b16 v[158:159], v146 offset:21504
	ds_read_b64_tr_b16 v[198:199], v146 offset:25600
	ds_read_b64_tr_b16 v[200:201], v146 offset:29696
	s_waitcnt lgkmcnt(0)
	v_mfma_f32_32x32x16_bf16 v[82:97], v[130:133], v[148:151], v[82:97]
	v_mfma_f32_32x32x16_bf16 v[82:97], v[134:137], v[152:155], v[82:97]
	v_mfma_f32_32x32x16_bf16 v[82:97], v[138:141], v[156:159], v[82:97]
	v_mfma_f32_32x32x16_bf16 v[82:97], v[142:145], v[198:201], v[82:97]
	ds_read_b64_tr_b16 v[148:149], v147 offset:50688
	ds_read_b64_tr_b16 v[150:151], v147 offset:54784
	ds_read_b64_tr_b16 v[152:153], v147 offset:58880
	ds_read_b64_tr_b16 v[154:155], v147 offset:62976
	ds_read_b64_tr_b16 v[156:157], v146 offset:17920
	ds_read_b64_tr_b16 v[158:159], v146 offset:22016
	ds_read_b64_tr_b16 v[198:199], v146 offset:26112
	ds_read_b64_tr_b16 v[200:201], v146 offset:30208
	s_waitcnt lgkmcnt(0)
	v_mfma_f32_32x32x16_bf16 v[66:81], v[130:133], v[148:151], v[66:81]
	v_mfma_f32_32x32x16_bf16 v[66:81], v[134:137], v[152:155], v[66:81]
	v_mfma_f32_32x32x16_bf16 v[66:81], v[138:141], v[156:159], v[66:81]
	v_mfma_f32_32x32x16_bf16 v[66:81], v[142:145], v[198:201], v[66:81]
	ds_read_b64_tr_b16 v[148:149], v147 offset:51200
	ds_read_b64_tr_b16 v[150:151], v147 offset:55296
	ds_read_b64_tr_b16 v[152:153], v147 offset:59392
	ds_read_b64_tr_b16 v[154:155], v147 offset:63488
	ds_read_b64_tr_b16 v[156:157], v146 offset:18432
	ds_read_b64_tr_b16 v[158:159], v146 offset:22528
	ds_read_b64_tr_b16 v[198:199], v146 offset:26624
	ds_read_b64_tr_b16 v[200:201], v146 offset:30720
	s_waitcnt lgkmcnt(0)
	v_mfma_f32_32x32x16_bf16 v[50:65], v[130:133], v[148:151], v[50:65]
	v_mfma_f32_32x32x16_bf16 v[50:65], v[134:137], v[152:155], v[50:65]
	v_mfma_f32_32x32x16_bf16 v[50:65], v[138:141], v[156:159], v[50:65]
	v_mfma_f32_32x32x16_bf16 v[50:65], v[142:145], v[198:201], v[50:65]
	ds_read_b64_tr_b16 v[148:149], v147 offset:51712
	ds_read_b64_tr_b16 v[150:151], v147 offset:55808
	ds_read_b64_tr_b16 v[152:153], v147 offset:59904
	ds_read_b64_tr_b16 v[154:155], v147 offset:64000
	ds_read_b64_tr_b16 v[156:157], v146 offset:18944
	ds_read_b64_tr_b16 v[158:159], v146 offset:23040
	ds_read_b64_tr_b16 v[198:199], v146 offset:27136
	ds_read_b64_tr_b16 v[200:201], v146 offset:31232
	s_waitcnt lgkmcnt(0)
	v_mfma_f32_32x32x16_bf16 v[34:49], v[130:133], v[148:151], v[34:49]
	v_mfma_f32_32x32x16_bf16 v[34:49], v[134:137], v[152:155], v[34:49]
	v_mfma_f32_32x32x16_bf16 v[34:49], v[138:141], v[156:159], v[34:49]
	v_mfma_f32_32x32x16_bf16 v[34:49], v[142:145], v[198:201], v[34:49]
	ds_read_b64_tr_b16 v[148:149], v147 offset:52224
	ds_read_b64_tr_b16 v[150:151], v147 offset:56320
	ds_read_b64_tr_b16 v[152:153], v147 offset:60416
	ds_read_b64_tr_b16 v[154:155], v147 offset:64512
	ds_read_b64_tr_b16 v[156:157], v146 offset:19456
	ds_read_b64_tr_b16 v[158:159], v146 offset:23552
	ds_read_b64_tr_b16 v[198:199], v146 offset:27648
	ds_read_b64_tr_b16 v[200:201], v146 offset:31744
	s_waitcnt lgkmcnt(0)
	v_mfma_f32_32x32x16_bf16 v[18:33], v[130:133], v[148:151], v[18:33]
	v_mfma_f32_32x32x16_bf16 v[18:33], v[134:137], v[152:155], v[18:33]
	v_mfma_f32_32x32x16_bf16 v[18:33], v[138:141], v[156:159], v[18:33]
	v_mfma_f32_32x32x16_bf16 v[18:33], v[142:145], v[198:201], v[18:33]
	ds_read_b64_tr_b16 v[148:149], v147 offset:52736
	ds_read_b64_tr_b16 v[150:151], v147 offset:56832
	ds_read_b64_tr_b16 v[152:153], v147 offset:60928
	ds_read_b64_tr_b16 v[154:155], v147 offset:65024
	ds_read_b64_tr_b16 v[156:157], v146 offset:19968
	ds_read_b64_tr_b16 v[158:159], v146 offset:24064
	ds_read_b64_tr_b16 v[198:199], v146 offset:28160
	ds_read_b64_tr_b16 v[200:201], v146 offset:32256
	s_waitcnt vmcnt(0)
	s_waitcnt lgkmcnt(0)
	s_barrier
	s_waitcnt lgkmcnt(0)
	v_mfma_f32_32x32x16_bf16 v[2:17], v[130:133], v[148:151], v[2:17]
	v_mfma_f32_32x32x16_bf16 v[2:17], v[134:137], v[152:155], v[2:17]
	v_add_u32_e32 v134, v218, v226
	ds_read_b128 v[130:133], v134 offset:32768
	ds_read_b128 v[134:137], v134 offset:40960
	v_mfma_f32_32x32x16_bf16 v[2:17], v[138:141], v[156:159], v[2:17]
	v_mfma_f32_32x32x16_bf16 v[2:17], v[142:145], v[198:201], v[2:17]
	s_waitcnt lgkmcnt(0)
	v_mfma_f32_32x32x16_bf16 v[146:161], v[130:133], v[190:193], 0
	v_mfma_f32_32x32x16_bf16 v[130:145], v[134:137], v[190:193], 0
	ds_read_b128 v[190:193], v195 offset:32768
	ds_read_b128 v[198:201], v195 offset:40960
	s_waitcnt lgkmcnt(0)
	v_mfma_f32_32x32x16_bf16 v[130:145], v[198:201], v[186:189], v[130:145]
	v_mfma_f32_32x32x16_bf16 v[146:161], v[190:193], v[186:189], v[146:161]
	v_add_u32_e32 v190, v218, v224
	ds_read_b128 v[186:189], v190 offset:32768
	ds_read_b128 v[190:193], v190 offset:40960
	s_waitcnt lgkmcnt(0)
	v_mfma_f32_32x32x16_bf16 v[130:145], v[190:193], v[182:185], v[130:145]
	v_mfma_f32_32x32x16_bf16 v[146:161], v[186:189], v[182:185], v[146:161]
	v_add_u32_e32 v186, v218, v223
	ds_read_b128 v[182:185], v186 offset:32768
	ds_read_b128 v[186:189], v186 offset:40960
	s_waitcnt lgkmcnt(0)
	v_mfma_f32_32x32x16_bf16 v[130:145], v[186:189], v[178:181], v[130:145]
	v_mfma_f32_32x32x16_bf16 v[146:161], v[182:185], v[178:181], v[146:161]
	v_add_u32_e32 v182, v218, v222
	ds_read_b128 v[178:181], v182 offset:32768
	ds_read_b128 v[182:185], v182 offset:40960
	s_waitcnt lgkmcnt(0)
	v_mfma_f32_32x32x16_bf16 v[130:145], v[182:185], v[174:177], v[130:145]
	v_mfma_f32_32x32x16_bf16 v[146:161], v[178:181], v[174:177], v[146:161]
	v_add_u32_e32 v178, v218, v221
	ds_read_b128 v[174:177], v178 offset:32768
	ds_read_b128 v[178:181], v178 offset:40960
	s_waitcnt lgkmcnt(0)
	v_mfma_f32_32x32x16_bf16 v[130:145], v[178:181], v[170:173], v[130:145]
	v_mfma_f32_32x32x16_bf16 v[146:161], v[174:177], v[170:173], v[146:161]
	v_add_u32_e32 v174, v218, v220
	ds_read_b128 v[170:173], v174 offset:32768
	ds_read_b128 v[174:177], v174 offset:40960
	s_waitcnt lgkmcnt(0)
	v_mfma_f32_32x32x16_bf16 v[130:145], v[174:177], v[166:169], v[130:145]
	v_mfma_f32_32x32x16_bf16 v[146:161], v[170:173], v[166:169], v[146:161]
	v_add_u32_e32 v170, v218, v219
	ds_read_b128 v[166:169], v170 offset:32768
	ds_read_b128 v[170:173], v170 offset:40960
	s_waitcnt lgkmcnt(0)
	v_mfma_f32_32x32x16_bf16 v[130:145], v[170:173], v[162:165], v[130:145]
	v_mfma_f32_32x32x16_bf16 v[146:161], v[166:169], v[162:165], v[146:161]
	s_nop 10
	v_fmamk_f32 v138, v138, 0x3e0293ee, v215
	v_fmamk_f32 v139, v139, 0x3e0293ee, v215
	v_fmamk_f32 v140, v140, 0x3e0293ee, v215
	v_fmamk_f32 v141, v141, 0x3e0293ee, v215
	v_fmamk_f32 v142, v142, 0x3e0293ee, v215
	v_exp_f32_e32 v162, v138
	v_fmamk_f32 v130, v130, 0x3e0293ee, v215
	v_fmamk_f32 v138, v155, 0x3e0293ee, v215
	v_exp_f32_e32 v155, v139
	v_fmamk_f32 v139, v156, 0x3e0293ee, v215
	v_exp_f32_e32 v156, v140
	v_fmamk_f32 v140, v157, 0x3e0293ee, v215
	v_exp_f32_e32 v157, v141
	v_fmamk_f32 v141, v158, 0x3e0293ee, v215
	v_exp_f32_e32 v158, v142
	v_fmamk_f32 v142, v159, 0x3e0293ee, v215
	v_fmamk_f32 v146, v146, 0x3e0293ee, v215
	v_exp_f32_e32 v159, v142
	v_fmamk_f32 v142, v143, 0x3e0293ee, v215
	v_exp_f32_e32 v146, v146
	v_fmamk_f32 v147, v147, 0x3e0293ee, v215
	v_exp_f32_e32 v163, v142
	v_fmamk_f32 v142, v160, 0x3e0293ee, v215
	v_exp_f32_e32 v147, v147
	v_fmamk_f32 v148, v148, 0x3e0293ee, v215
	v_exp_f32_e32 v160, v142
	v_fmamk_f32 v142, v144, 0x3e0293ee, v215
	v_exp_f32_e32 v148, v148
	v_fmamk_f32 v149, v149, 0x3e0293ee, v215
	v_exp_f32_e32 v164, v142
	v_fmamk_f32 v142, v161, 0x3e0293ee, v215
	v_exp_f32_e32 v149, v149
	v_fmamk_f32 v150, v150, 0x3e0293ee, v215
	v_exp_f32_e32 v161, v142
	v_fmamk_f32 v142, v145, 0x3e0293ee, v215
	v_exp_f32_e32 v150, v150
	v_fmamk_f32 v151, v151, 0x3e0293ee, v215
	v_exp_f32_e32 v165, v142
	v_add_f32_e32 v142, 0, v146
	v_exp_f32_e32 v151, v151
	v_fmamk_f32 v152, v152, 0x3e0293ee, v215
	v_add_f32_e32 v142, v147, v142
	v_exp_f32_e32 v152, v152
	v_fmamk_f32 v153, v153, 0x3e0293ee, v215
	v_add_f32_e32 v142, v148, v142
	v_exp_f32_e32 v153, v153
	v_fmamk_f32 v154, v154, 0x3e0293ee, v215
	v_add_f32_e32 v142, v149, v142
	v_exp_f32_e32 v154, v154
	v_add_f32_e32 v142, v150, v142
	v_exp_f32_e32 v138, v138
	v_add_f32_e32 v142, v151, v142
	v_exp_f32_e32 v139, v139
	v_add_f32_e32 v142, v152, v142
	v_exp_f32_e32 v140, v140
	v_add_f32_e32 v142, v153, v142
	v_exp_f32_e32 v141, v141
	v_add_f32_e32 v142, v154, v142
	v_add_f32_e32 v142, v138, v142
	v_add_f32_e32 v142, v139, v142
	v_add_f32_e32 v142, v140, v142
	v_exp_f32_e32 v130, v130
	v_fmamk_f32 v131, v131, 0x3e0293ee, v215
	v_add_f32_e32 v142, v141, v142
	v_exp_f32_e32 v131, v131
	v_fmamk_f32 v132, v132, 0x3e0293ee, v215
	v_add_f32_e32 v142, v159, v142
	v_exp_f32_e32 v132, v132
	v_fmamk_f32 v133, v133, 0x3e0293ee, v215
	v_add_f32_e32 v142, v160, v142
	v_exp_f32_e32 v133, v133
	v_fmamk_f32 v134, v134, 0x3e0293ee, v215
	v_add_f32_e32 v142, v161, v142
	v_exp_f32_e32 v134, v134
	v_fmamk_f32 v135, v135, 0x3e0293ee, v215
	v_add_f32_e32 v142, v130, v142
	v_exp_f32_e32 v135, v135
	v_fmamk_f32 v136, v136, 0x3e0293ee, v215
	v_add_f32_e32 v142, v131, v142
	v_exp_f32_e32 v136, v136
	v_fmamk_f32 v137, v137, 0x3e0293ee, v215
	v_add_f32_e32 v142, v132, v142
	v_exp_f32_e32 v137, v137
	v_add_f32_e32 v142, v133, v142
	v_add_f32_e32 v142, v134, v142
	v_add_f32_e32 v142, v135, v142
	v_add_f32_e32 v142, v136, v142
	v_add_f32_e32 v142, v137, v142
	v_add_f32_e32 v142, v162, v142
	v_add_f32_e32 v142, v155, v142
	v_add_f32_e32 v142, v156, v142
	v_add_f32_e32 v142, v157, v142
	v_add_f32_e32 v142, v158, v142
	v_add_f32_e32 v142, v163, v142
	v_add_f32_e32 v142, v164, v142
	v_add_f32_e32 v195, v165, v142
	v_cvt_pk_bf16_f32 v142, v146, v147
	v_cvt_pk_bf16_f32 v143, v148, v149
	v_cvt_pk_bf16_f32 v144, v150, v151
	v_cvt_pk_bf16_f32 v145, v152, v153
	v_add_u32_e32 v146, 0x1c000, v217
	v_add_u32_e32 v148, 0x1d000, v217
	v_permlane32_swap_b32_e32 v142, v144
	v_permlane32_swap_b32_e32 v143, v145
	ds_read_b64_tr_b16 v[146:147], v146
	ds_read_b64_tr_b16 v[148:149], v148
	v_add_u32_e32 v150, 0x1e000, v217
	v_add_u32_e32 v152, 0x1f000, v217
	ds_read_b64_tr_b16 v[150:151], v150
	ds_read_b64_tr_b16 v[152:153], v152
	s_waitcnt lgkmcnt(0)
	v_mfma_f32_32x32x16_bf16 v[114:129], v[142:145], v[146:149], v[114:129]
	v_cvt_pk_bf16_f32 v138, v154, v138
	v_cvt_pk_bf16_f32 v139, v139, v140
	v_cvt_pk_bf16_f32 v140, v141, v159
	v_cvt_pk_bf16_f32 v141, v160, v161
	s_nop 0
	v_permlane32_swap_b32_e32 v138, v140
	v_permlane32_swap_b32_e32 v139, v141
	v_add_u32_e32 v146, 0x1c200, v217
	v_add_u32_e32 v148, 0x1d200, v217
	ds_read_b64_tr_b16 v[146:147], v146
	ds_read_b64_tr_b16 v[148:149], v148
	v_mfma_f32_32x32x16_bf16 v[114:129], v[138:141], v[150:153], v[114:129]
	v_add_u32_e32 v150, 0x1e200, v217
	v_add_u32_e32 v152, 0x1f200, v217
	ds_read_b64_tr_b16 v[150:151], v150
	ds_read_b64_tr_b16 v[152:153], v152
	v_cvt_pk_bf16_f32 v130, v130, v131
	v_cvt_pk_bf16_f32 v131, v132, v133
	v_cvt_pk_bf16_f32 v132, v134, v135
	s_waitcnt lgkmcnt(0)
	v_mfma_f32_32x32x16_bf16 v[98:113], v[142:145], v[146:149], v[98:113]
	v_cvt_pk_bf16_f32 v133, v136, v137
	v_cvt_pk_bf16_f32 v135, v156, v157
	v_add_u32_e32 v154, 0x20000, v217
	v_add_u32_e32 v156, 0x21000, v217
	v_permlane32_swap_b32_e32 v130, v132
	v_permlane32_swap_b32_e32 v131, v133
	v_cvt_pk_bf16_f32 v134, v162, v155
	ds_read_b64_tr_b16 v[154:155], v154
	ds_read_b64_tr_b16 v[156:157], v156
	v_add_u32_e32 v146, 0x1c400, v217
	v_add_u32_e32 v148, 0x1d400, v217
	ds_read_b64_tr_b16 v[146:147], v146
	ds_read_b64_tr_b16 v[148:149], v148
	v_cvt_pk_bf16_f32 v136, v158, v163
	v_add_u32_e32 v158, 0x22000, v217
	v_add_u32_e32 v160, 0x23000, v217
	ds_read_b64_tr_b16 v[158:159], v158
	ds_read_b64_tr_b16 v[160:161], v160
	s_waitcnt lgkmcnt(0)
	v_mfma_f32_32x32x16_bf16 v[114:129], v[130:133], v[154:157], v[114:129]
	v_cvt_pk_bf16_f32 v137, v164, v165
	v_permlane32_swap_b32_e32 v134, v136
	s_nop 0
	v_permlane32_swap_b32_e32 v135, v137
	v_add_u32_e32 v154, 0x20200, v217
	v_add_u32_e32 v156, 0x21200, v217
	v_mfma_f32_32x32x16_bf16 v[98:113], v[138:141], v[150:153], v[98:113]
	v_add_u32_e32 v150, 0x1e400, v217
	v_add_u32_e32 v152, 0x1f400, v217
	ds_read_b64_tr_b16 v[150:151], v150
	ds_read_b64_tr_b16 v[152:153], v152
	ds_read_b64_tr_b16 v[154:155], v154
	ds_read_b64_tr_b16 v[156:157], v156
	v_mov_b32_e32 v197, v195
	v_mfma_f32_32x32x16_bf16 v[82:97], v[142:145], v[146:149], v[82:97]
	v_add_u32_e32 v146, 0x1c600, v217
	v_add_u32_e32 v148, 0x1d600, v217
	ds_read_b64_tr_b16 v[146:147], v146
	ds_read_b64_tr_b16 v[148:149], v148
	v_permlane32_swap_b32_e32 v195, v197
	v_mfma_f32_32x32x16_bf16 v[114:129], v[134:137], v[158:161], v[114:129]
	v_add_u32_e32 v158, 0x22200, v217
	v_add_u32_e32 v160, 0x23200, v217
	ds_read_b64_tr_b16 v[158:159], v158
	ds_read_b64_tr_b16 v[160:161], v160
	s_waitcnt lgkmcnt(0)
	v_mfma_f32_32x32x16_bf16 v[98:113], v[130:133], v[154:157], v[98:113]
	v_add_u32_e32 v154, 0x20400, v217
	v_add_u32_e32 v156, 0x21400, v217
	ds_read_b64_tr_b16 v[154:155], v154
	ds_read_b64_tr_b16 v[156:157], v156
	v_mfma_f32_32x32x16_bf16 v[82:97], v[138:141], v[150:153], v[82:97]
	v_add_u32_e32 v150, 0x1e600, v217
	v_add_u32_e32 v152, 0x1f600, v217
	ds_read_b64_tr_b16 v[150:151], v150
	ds_read_b64_tr_b16 v[152:153], v152
	v_mfma_f32_32x32x16_bf16 v[66:81], v[142:145], v[146:149], v[66:81]
	v_add_u32_e32 v146, 0x1c800, v217
	v_add_u32_e32 v148, 0x1d800, v217
	ds_read_b64_tr_b16 v[146:147], v146
	ds_read_b64_tr_b16 v[148:149], v148
	v_mfma_f32_32x32x16_bf16 v[98:113], v[134:137], v[158:161], v[98:113]
	v_add_u32_e32 v158, 0x22400, v217
	v_add_u32_e32 v160, 0x23400, v217
	ds_read_b64_tr_b16 v[158:159], v158
	ds_read_b64_tr_b16 v[160:161], v160
	s_waitcnt lgkmcnt(0)
	v_mfma_f32_32x32x16_bf16 v[82:97], v[130:133], v[154:157], v[82:97]
	v_add_u32_e32 v154, 0x20600, v217
	v_add_u32_e32 v156, 0x21600, v217
	ds_read_b64_tr_b16 v[154:155], v154
	ds_read_b64_tr_b16 v[156:157], v156
	v_mfma_f32_32x32x16_bf16 v[66:81], v[138:141], v[150:153], v[66:81]
	v_add_u32_e32 v150, 0x1e800, v217
	v_add_u32_e32 v152, 0x1f800, v217
	ds_read_b64_tr_b16 v[150:151], v150
	ds_read_b64_tr_b16 v[152:153], v152
	v_mfma_f32_32x32x16_bf16 v[50:65], v[142:145], v[146:149], v[50:65]
	v_add_u32_e32 v146, 0x1ca00, v217
	v_add_u32_e32 v148, 0x1da00, v217
	ds_read_b64_tr_b16 v[146:147], v146
	ds_read_b64_tr_b16 v[148:149], v148
	v_mfma_f32_32x32x16_bf16 v[82:97], v[134:137], v[158:161], v[82:97]
	v_add_u32_e32 v158, 0x22600, v217
	v_add_u32_e32 v160, 0x23600, v217
	ds_read_b64_tr_b16 v[158:159], v158
	ds_read_b64_tr_b16 v[160:161], v160
	s_waitcnt lgkmcnt(0)
	v_mfma_f32_32x32x16_bf16 v[66:81], v[130:133], v[154:157], v[66:81]
	v_add_u32_e32 v154, 0x20800, v217
	v_add_u32_e32 v156, 0x21800, v217
	ds_read_b64_tr_b16 v[154:155], v154
	ds_read_b64_tr_b16 v[156:157], v156
	v_mfma_f32_32x32x16_bf16 v[50:65], v[138:141], v[150:153], v[50:65]
	v_add_u32_e32 v150, 0x1ea00, v217
	v_add_u32_e32 v152, 0x1fa00, v217
	ds_read_b64_tr_b16 v[150:151], v150
	ds_read_b64_tr_b16 v[152:153], v152
	v_mfma_f32_32x32x16_bf16 v[34:49], v[142:145], v[146:149], v[34:49]
	v_add_u32_e32 v146, 0x1cc00, v217
	v_add_u32_e32 v148, 0x1dc00, v217
	ds_read_b64_tr_b16 v[146:147], v146
	ds_read_b64_tr_b16 v[148:149], v148
	v_mfma_f32_32x32x16_bf16 v[66:81], v[134:137], v[158:161], v[66:81]
	v_add_u32_e32 v158, 0x22800, v217
	v_add_u32_e32 v160, 0x23800, v217
	ds_read_b64_tr_b16 v[158:159], v158
	ds_read_b64_tr_b16 v[160:161], v160
	s_waitcnt lgkmcnt(0)
	v_mfma_f32_32x32x16_bf16 v[50:65], v[130:133], v[154:157], v[50:65]
	v_add_u32_e32 v154, 0x20a00, v217
	v_add_u32_e32 v156, 0x21a00, v217
	ds_read_b64_tr_b16 v[154:155], v154
	ds_read_b64_tr_b16 v[156:157], v156
	v_mfma_f32_32x32x16_bf16 v[34:49], v[138:141], v[150:153], v[34:49]
	v_add_u32_e32 v150, 0x1ec00, v217
	v_add_u32_e32 v152, 0x1fc00, v217
	ds_read_b64_tr_b16 v[150:151], v150
	ds_read_b64_tr_b16 v[152:153], v152
	v_mfma_f32_32x32x16_bf16 v[18:33], v[142:145], v[146:149], v[18:33]
	v_add_u32_e32 v146, 0x1ce00, v217
	v_add_u32_e32 v148, 0x1de00, v217
	ds_read_b64_tr_b16 v[146:147], v146
	ds_read_b64_tr_b16 v[148:149], v148
	v_mfma_f32_32x32x16_bf16 v[50:65], v[134:137], v[158:161], v[50:65]
	v_add_u32_e32 v158, 0x22a00, v217
	v_add_u32_e32 v160, 0x23a00, v217
	ds_read_b64_tr_b16 v[158:159], v158
	ds_read_b64_tr_b16 v[160:161], v160
	s_waitcnt lgkmcnt(0)
	v_mfma_f32_32x32x16_bf16 v[34:49], v[130:133], v[154:157], v[34:49]
	v_add_u32_e32 v154, 0x20c00, v217
	v_add_u32_e32 v156, 0x21c00, v217
	ds_read_b64_tr_b16 v[154:155], v154
	ds_read_b64_tr_b16 v[156:157], v156
	v_mfma_f32_32x32x16_bf16 v[18:33], v[138:141], v[150:153], v[18:33]
	v_add_u32_e32 v150, 0x1ee00, v217
	v_add_u32_e32 v152, 0x1fe00, v217
	ds_read_b64_tr_b16 v[150:151], v150
	ds_read_b64_tr_b16 v[152:153], v152
	v_mfma_f32_32x32x16_bf16 v[2:17], v[142:145], v[146:149], v[2:17]
	v_mfma_f32_32x32x16_bf16 v[34:49], v[134:137], v[158:161], v[34:49]
	v_add_u32_e32 v158, 0x22c00, v217
	v_add_u32_e32 v160, 0x23c00, v217
	ds_read_b64_tr_b16 v[158:159], v158
	ds_read_b64_tr_b16 v[160:161], v160
	s_waitcnt lgkmcnt(0)
	v_mfma_f32_32x32x16_bf16 v[18:33], v[130:133], v[154:157], v[18:33]
	v_add_u32_e32 v154, 0x20e00, v217
	v_add_u32_e32 v156, 0x21e00, v217
	ds_read_b64_tr_b16 v[154:155], v154
	ds_read_b64_tr_b16 v[156:157], v156
	v_mfma_f32_32x32x16_bf16 v[2:17], v[138:141], v[150:153], v[2:17]
	v_mfma_f32_32x32x16_bf16 v[18:33], v[134:137], v[158:161], v[18:33]
	v_add_u32_e32 v158, 0x22e00, v217
	v_add_u32_e32 v160, 0x23e00, v217
	ds_read_b64_tr_b16 v[158:159], v158
	ds_read_b64_tr_b16 v[160:161], v160
	s_waitcnt vmcnt(0) lgkmcnt(0)
	s_barrier
	v_mfma_f32_32x32x16_bf16 v[2:17], v[130:133], v[154:157], v[2:17]
	v_mfma_f32_32x32x16_bf16 v[2:17], v[134:137], v[158:161], v[2:17]
	s_and_saveexec_b64 s[2:3], vcc
	s_cbranch_execz .LBB0_1212
	v_pk_add_f32 v[130:131], v[194:195], v[196:197]
	s_nop 0
	v_add_f32_e32 v130, v211, v130
	v_add_f32_e32 v130, v130, v131
	v_lshl_add_u32 v131, v205, 2, s93
	ds_write_b32 v131, v130
	s_branch .LBB0_1212
